# K-loops: counted lgkmcnt per MFMA; second-k-half B fragment reads issued after the phase barrier inside the compute segment
# baseline (speedup 1.0000x reference)
.LBB0_119:
	s_add_u32 s26, s6, 0xfff80080
	s_addc_u32 s27, s7, -1
	s_add_i32 s66, 0, 0x10000
	v_add_u32_e32 v44, s66, v194
	ds_read_b128 v[24:27], v44
	ds_read_b128 v[32:35], v44 offset:1024
	ds_read_b128 v[40:43], v44 offset:2048
	ds_read_b128 v[44:47], v44 offset:3072
	s_cmp_eq_u32 s57, 28
	s_cselect_b32 s29, s25, s27
	s_cselect_b32 s28, s24, s26
	s_cselect_b32 s27, s9, s19
	s_cselect_b32 s26, s8, s11
	v_lshl_add_u64 v[180:181], s[6:7], 0, v[168:169]
	s_add_i32 m0, s36, 0xc000
	ds_read_b128 v[172:175], v196
	ds_read_b128 v[198:201], v196 offset:2048
	ds_read_b128 v[206:209], v196 offset:4096
	ds_read_b128 v[214:217], v196 offset:6144
	global_load_lds_dwordx4 v[180:181], off
	v_lshl_add_u64 v[180:181], s[6:7], 0, v[170:171]
	s_add_i32 m0, s36, 0xe000
	s_nop 0
	global_load_lds_dwordx4 v[180:181], off
	s_waitcnt lgkmcnt(4)
	s_barrier
	s_setprio 1
	ds_read_b128 v[176:179], v196 offset:1024
	ds_read_b128 v[202:205], v196 offset:3072
	ds_read_b128 v[210:213], v196 offset:5120
	ds_read_b128 v[218:221], v196 offset:7168
	s_waitcnt lgkmcnt(7)
	v_mfma_f32_16x16x32_bf16 v[140:143], v[24:27], v[172:175], v[140:143]
	v_mfma_f32_16x16x32_bf16 v[136:139], v[40:43], v[172:175], v[136:139]
	s_waitcnt lgkmcnt(6)
	v_mfma_f32_16x16x32_bf16 v[124:127], v[24:27], v[198:201], v[124:127]
	v_mfma_f32_16x16x32_bf16 v[120:123], v[40:43], v[198:201], v[120:123]
	s_waitcnt lgkmcnt(5)
	v_mfma_f32_16x16x32_bf16 v[108:111], v[24:27], v[206:209], v[108:111]
	v_mfma_f32_16x16x32_bf16 v[104:107], v[40:43], v[206:209], v[104:107]
	s_waitcnt lgkmcnt(4)
	v_mfma_f32_16x16x32_bf16 v[92:95], v[24:27], v[214:217], v[92:95]
	v_mfma_f32_16x16x32_bf16 v[88:91], v[40:43], v[214:217], v[88:91]
	s_waitcnt lgkmcnt(3)
	v_mfma_f32_16x16x32_bf16 v[140:143], v[32:35], v[176:179], v[140:143]
	v_mfma_f32_16x16x32_bf16 v[136:139], v[44:47], v[176:179], v[136:139]
	s_waitcnt lgkmcnt(2)
	v_mfma_f32_16x16x32_bf16 v[124:127], v[32:35], v[202:205], v[124:127]
	v_mfma_f32_16x16x32_bf16 v[120:123], v[44:47], v[202:205], v[120:123]
	s_waitcnt lgkmcnt(1)
	v_mfma_f32_16x16x32_bf16 v[108:111], v[32:35], v[210:213], v[108:111]
	v_mfma_f32_16x16x32_bf16 v[104:107], v[44:47], v[210:213], v[104:107]
	s_waitcnt lgkmcnt(0)
	v_mfma_f32_16x16x32_bf16 v[92:95], v[32:35], v[218:221], v[92:95]
	v_mfma_f32_16x16x32_bf16 v[88:91], v[44:47], v[218:221], v[88:91]
	s_setprio 0
	s_barrier
	s_add_i32 s70, 0, 0x14000
	v_add_u32_e32 v180, s70, v194
	s_add_i32 s66, s66, s35
	ds_read_b128 v[222:225], v180
	ds_read_b128 v[226:229], v180 offset:1024
	ds_read_b128 v[230:233], v180 offset:2048
	ds_read_b128 v[234:237], v180 offset:3072
	v_lshl_add_u64 v[180:181], s[26:27], 0, v[144:145]
	s_mov_b32 m0, s66
	v_lshl_add_u64 v[238:239], s[26:27], 0, v[166:167]
	global_load_lds_dwordx4 v[180:181], off
	s_add_i32 m0, s66, 0x2000
	s_nop 0
	global_load_lds_dwordx4 v[238:239], off
	s_barrier
	s_setprio 1
	s_waitcnt lgkmcnt(3)
	v_mfma_f32_16x16x32_bf16 v[132:135], v[222:225], v[172:175], v[132:135]
	s_waitcnt lgkmcnt(1)
	v_mfma_f32_16x16x32_bf16 v[128:131], v[230:233], v[172:175], v[128:131]
	v_mfma_f32_16x16x32_bf16 v[116:119], v[222:225], v[198:201], v[116:119]
	v_mfma_f32_16x16x32_bf16 v[112:115], v[230:233], v[198:201], v[112:115]
	v_mfma_f32_16x16x32_bf16 v[100:103], v[222:225], v[206:209], v[100:103]
	v_mfma_f32_16x16x32_bf16 v[96:99], v[230:233], v[206:209], v[96:99]
	v_mfma_f32_16x16x32_bf16 v[84:87], v[222:225], v[214:217], v[84:87]
	v_mfma_f32_16x16x32_bf16 v[80:83], v[230:233], v[214:217], v[80:83]
	v_mfma_f32_16x16x32_bf16 v[132:135], v[226:229], v[176:179], v[132:135]
	s_waitcnt lgkmcnt(0)
	v_mfma_f32_16x16x32_bf16 v[128:131], v[234:237], v[176:179], v[128:131]
	v_mfma_f32_16x16x32_bf16 v[116:119], v[226:229], v[202:205], v[116:119]
	v_mfma_f32_16x16x32_bf16 v[112:115], v[234:237], v[202:205], v[112:115]
	v_mfma_f32_16x16x32_bf16 v[100:103], v[226:229], v[210:213], v[100:103]
	v_mfma_f32_16x16x32_bf16 v[96:99], v[234:237], v[210:213], v[96:99]
	v_mfma_f32_16x16x32_bf16 v[84:87], v[226:229], v[218:221], v[84:87]
	v_mfma_f32_16x16x32_bf16 v[80:83], v[234:237], v[218:221], v[80:83]
	s_setprio 0
	s_mov_b32 m0, s36
	v_lshl_add_u64 v[240:241], s[28:29], 0, v[162:163]
	s_barrier
	ds_read_b128 v[172:175], v196 offset:16384
	ds_read_b128 v[176:179], v196 offset:17408
	ds_read_b128 v[198:201], v196 offset:18432
	ds_read_b128 v[202:205], v196 offset:19456
	ds_read_b128 v[206:209], v196 offset:20480
	ds_read_b128 v[210:213], v196 offset:21504
	ds_read_b128 v[214:217], v196 offset:22528
	ds_read_b128 v[218:221], v196 offset:23552
	global_load_lds_dwordx4 v[240:241], off
	v_lshl_add_u64 v[242:243], s[28:29], 0, v[164:165]
	s_mov_b32 m0, s37
	s_nop 0
	global_load_lds_dwordx4 v[242:243], off
	s_barrier
	s_setprio 1
	s_waitcnt lgkmcnt(7)
	v_mfma_f32_16x16x32_bf16 v[76:79], v[24:27], v[172:175], v[76:79]
	v_mfma_f32_16x16x32_bf16 v[72:75], v[40:43], v[172:175], v[72:75]
	s_waitcnt lgkmcnt(5)
	v_mfma_f32_16x16x32_bf16 v[60:63], v[24:27], v[198:201], v[60:63]
	v_mfma_f32_16x16x32_bf16 v[56:59], v[40:43], v[198:201], v[56:59]
	s_waitcnt lgkmcnt(3)
	v_mfma_f32_16x16x32_bf16 v[36:39], v[24:27], v[206:209], v[36:39]
	v_mfma_f32_16x16x32_bf16 v[28:31], v[40:43], v[206:209], v[28:31]
	s_waitcnt lgkmcnt(1)
	v_mfma_f32_16x16x32_bf16 v[12:15], v[24:27], v[214:217], v[12:15]
	v_mfma_f32_16x16x32_bf16 v[8:11], v[40:43], v[214:217], v[8:11]
	v_mfma_f32_16x16x32_bf16 v[76:79], v[32:35], v[176:179], v[76:79]
	v_mfma_f32_16x16x32_bf16 v[72:75], v[44:47], v[176:179], v[72:75]
	v_mfma_f32_16x16x32_bf16 v[60:63], v[32:35], v[202:205], v[60:63]
	v_mfma_f32_16x16x32_bf16 v[56:59], v[44:47], v[202:205], v[56:59]
	v_mfma_f32_16x16x32_bf16 v[36:39], v[32:35], v[210:213], v[36:39]
	v_mfma_f32_16x16x32_bf16 v[28:31], v[44:47], v[210:213], v[28:31]
	s_waitcnt lgkmcnt(0)
	v_mfma_f32_16x16x32_bf16 v[12:15], v[32:35], v[218:221], v[12:15]
	v_mfma_f32_16x16x32_bf16 v[8:11], v[44:47], v[218:221], v[8:11]
	s_setprio 0
	s_barrier
	s_add_u32 s66, s26, 0x80000
	s_addc_u32 s67, s27, 0
	s_add_i32 s70, s70, s35
	v_lshl_add_u64 v[24:25], s[66:67], 0, v[144:145]
	s_mov_b32 m0, s70
	s_nop 0
	global_load_lds_dwordx4 v[24:25], off
	v_lshl_add_u64 v[24:25], s[66:67], 0, v[166:167]
	s_add_i32 m0, s70, 0x2000
	s_nop 0
	global_load_lds_dwordx4 v[24:25], off
	s_waitcnt vmcnt(6)
	s_barrier
	s_setprio 1
	v_mfma_f32_16x16x32_bf16 v[20:23], v[222:225], v[206:209], v[20:23]
	v_mfma_f32_16x16x32_bf16 v[16:19], v[230:233], v[206:209], v[16:19]
	v_mfma_f32_16x16x32_bf16 v[4:7], v[222:225], v[214:217], v[4:7]
	v_mfma_f32_16x16x32_bf16 v[0:3], v[230:233], v[214:217], v[0:3]
	v_mfma_f32_16x16x32_bf16 v[24:27], v[222:225], v[172:175], v[68:71]
	v_mfma_f32_16x16x32_bf16 v[32:35], v[230:233], v[172:175], v[64:67]
	v_mfma_f32_16x16x32_bf16 v[40:43], v[222:225], v[198:201], v[52:55]
	v_mfma_f32_16x16x32_bf16 v[44:47], v[230:233], v[198:201], v[48:51]
	v_mfma_f32_16x16x32_bf16 v[20:23], v[226:229], v[210:213], v[20:23]
	v_mfma_f32_16x16x32_bf16 v[16:19], v[234:237], v[210:213], v[16:19]
	v_mfma_f32_16x16x32_bf16 v[4:7], v[226:229], v[218:221], v[4:7]
	v_mfma_f32_16x16x32_bf16 v[0:3], v[234:237], v[218:221], v[0:3]
	v_mfma_f32_16x16x32_bf16 v[24:27], v[226:229], v[176:179], v[24:27]
	v_mfma_f32_16x16x32_bf16 v[32:35], v[234:237], v[176:179], v[32:35]
	v_mfma_f32_16x16x32_bf16 v[40:43], v[226:229], v[202:205], v[40:43]
	v_mfma_f32_16x16x32_bf16 v[44:47], v[234:237], v[202:205], v[44:47]
	s_setprio 0
	s_add_i32 s66, 0, 0x18000
	v_add_u32_e32 v68, s66, v194
	s_barrier
	ds_read_b128 v[48:51], v68
	ds_read_b128 v[52:55], v68 offset:1024
	ds_read_b128 v[64:67], v68 offset:2048
	ds_read_b128 v[68:71], v68 offset:3072
	s_add_u32 s28, s28, 0x80000
	s_addc_u32 s29, s29, 0
	s_mov_b32 m0, s50
	v_lshl_add_u64 v[222:223], s[28:29], 0, v[162:163]
	ds_read_b128 v[172:175], v196 offset:32768
	ds_read_b128 v[198:201], v196 offset:34816
	ds_read_b128 v[206:209], v196 offset:36864
	ds_read_b128 v[214:217], v196 offset:38912
	global_load_lds_dwordx4 v[222:223], off
	v_lshl_add_u64 v[222:223], s[28:29], 0, v[164:165]
	s_mov_b32 m0, s51
	s_nop 0
	global_load_lds_dwordx4 v[222:223], off
	s_waitcnt lgkmcnt(4)
	s_barrier
	s_setprio 1
	ds_read_b128 v[176:179], v196 offset:33792
	ds_read_b128 v[202:205], v196 offset:35840
	ds_read_b128 v[210:213], v196 offset:37888
	ds_read_b128 v[218:221], v196 offset:39936
	s_waitcnt lgkmcnt(7)
	v_mfma_f32_16x16x32_bf16 v[140:143], v[48:51], v[172:175], v[140:143]
	v_mfma_f32_16x16x32_bf16 v[136:139], v[64:67], v[172:175], v[136:139]
	s_waitcnt lgkmcnt(6)
	v_mfma_f32_16x16x32_bf16 v[124:127], v[48:51], v[198:201], v[124:127]
	v_mfma_f32_16x16x32_bf16 v[120:123], v[64:67], v[198:201], v[120:123]
	s_waitcnt lgkmcnt(5)
	v_mfma_f32_16x16x32_bf16 v[108:111], v[48:51], v[206:209], v[108:111]
	v_mfma_f32_16x16x32_bf16 v[104:107], v[64:67], v[206:209], v[104:107]
	s_waitcnt lgkmcnt(4)
	v_mfma_f32_16x16x32_bf16 v[92:95], v[48:51], v[214:217], v[92:95]
	v_mfma_f32_16x16x32_bf16 v[88:91], v[64:67], v[214:217], v[88:91]
	s_waitcnt lgkmcnt(3)
	v_mfma_f32_16x16x32_bf16 v[140:143], v[52:55], v[176:179], v[140:143]
	v_mfma_f32_16x16x32_bf16 v[136:139], v[68:71], v[176:179], v[136:139]
	s_waitcnt lgkmcnt(2)
	v_mfma_f32_16x16x32_bf16 v[124:127], v[52:55], v[202:205], v[124:127]
	v_mfma_f32_16x16x32_bf16 v[120:123], v[68:71], v[202:205], v[120:123]
	s_waitcnt lgkmcnt(1)
	v_mfma_f32_16x16x32_bf16 v[108:111], v[52:55], v[210:213], v[108:111]
	v_mfma_f32_16x16x32_bf16 v[104:107], v[68:71], v[210:213], v[104:107]
	s_waitcnt lgkmcnt(0)
	v_mfma_f32_16x16x32_bf16 v[92:95], v[52:55], v[218:221], v[92:95]
	v_mfma_f32_16x16x32_bf16 v[88:91], v[68:71], v[218:221], v[88:91]
	s_setprio 0
	s_barrier
	s_add_i32 s28, 0, 0x1c000
	s_add_i32 s29, s66, s35
	v_add_u32_e32 v197, s28, v194
	v_lshl_add_u64 v[180:181], v[180:181], 0, s[86:87]
	s_mov_b32 m0, s29
	ds_read_b128 v[222:225], v197
	ds_read_b128 v[226:229], v197 offset:1024
	ds_read_b128 v[230:233], v197 offset:2048
	ds_read_b128 v[234:237], v197 offset:3072
	global_load_lds_dwordx4 v[180:181], off
	v_lshl_add_u64 v[180:181], v[238:239], 0, s[86:87]
	s_add_i32 m0, s29, 0x2000
	s_nop 0
	global_load_lds_dwordx4 v[180:181], off
	s_barrier
	s_setprio 1
	s_waitcnt lgkmcnt(3)
	v_mfma_f32_16x16x32_bf16 v[132:135], v[222:225], v[172:175], v[132:135]
	s_waitcnt lgkmcnt(1)
	v_mfma_f32_16x16x32_bf16 v[128:131], v[230:233], v[172:175], v[128:131]
	v_mfma_f32_16x16x32_bf16 v[116:119], v[222:225], v[198:201], v[116:119]
	v_mfma_f32_16x16x32_bf16 v[112:115], v[230:233], v[198:201], v[112:115]
	v_mfma_f32_16x16x32_bf16 v[100:103], v[222:225], v[206:209], v[100:103]
	v_mfma_f32_16x16x32_bf16 v[96:99], v[230:233], v[206:209], v[96:99]
	v_mfma_f32_16x16x32_bf16 v[84:87], v[222:225], v[214:217], v[84:87]
	v_mfma_f32_16x16x32_bf16 v[80:83], v[230:233], v[214:217], v[80:83]
	v_mfma_f32_16x16x32_bf16 v[132:135], v[226:229], v[176:179], v[132:135]
	s_waitcnt lgkmcnt(0)
	v_mfma_f32_16x16x32_bf16 v[128:131], v[234:237], v[176:179], v[128:131]
	v_mfma_f32_16x16x32_bf16 v[116:119], v[226:229], v[202:205], v[116:119]
	v_mfma_f32_16x16x32_bf16 v[112:115], v[234:237], v[202:205], v[112:115]
	v_mfma_f32_16x16x32_bf16 v[100:103], v[226:229], v[210:213], v[100:103]
	v_mfma_f32_16x16x32_bf16 v[96:99], v[234:237], v[210:213], v[96:99]
	v_mfma_f32_16x16x32_bf16 v[84:87], v[226:229], v[218:221], v[84:87]
	v_mfma_f32_16x16x32_bf16 v[80:83], v[234:237], v[218:221], v[80:83]
	s_setprio 0
	s_mov_b32 m0, s52
	v_lshl_add_u64 v[180:181], v[240:241], 0, s[86:87]
	s_barrier
	ds_read_b128 v[172:175], v196 offset:49152
	ds_read_b128 v[176:179], v196 offset:50176
	ds_read_b128 v[198:201], v196 offset:51200
	ds_read_b128 v[202:205], v196 offset:52224
	ds_read_b128 v[206:209], v196 offset:53248
	ds_read_b128 v[210:213], v196 offset:54272
	ds_read_b128 v[214:217], v196 offset:55296
	ds_read_b128 v[218:221], v196 offset:56320
	global_load_lds_dwordx4 v[180:181], off
	v_lshl_add_u64 v[180:181], v[242:243], 0, s[86:87]
	s_mov_b32 m0, s53
	s_nop 0
	global_load_lds_dwordx4 v[180:181], off
	s_barrier
	s_setprio 1
	s_waitcnt lgkmcnt(7)
	v_mfma_f32_16x16x32_bf16 v[76:79], v[48:51], v[172:175], v[76:79]
	v_mfma_f32_16x16x32_bf16 v[72:75], v[64:67], v[172:175], v[72:75]
	s_waitcnt lgkmcnt(5)
	v_mfma_f32_16x16x32_bf16 v[60:63], v[48:51], v[198:201], v[60:63]
	v_mfma_f32_16x16x32_bf16 v[56:59], v[64:67], v[198:201], v[56:59]
	s_waitcnt lgkmcnt(3)
	v_mfma_f32_16x16x32_bf16 v[36:39], v[48:51], v[206:209], v[36:39]
	v_mfma_f32_16x16x32_bf16 v[28:31], v[64:67], v[206:209], v[28:31]
	s_waitcnt lgkmcnt(1)
	v_mfma_f32_16x16x32_bf16 v[12:15], v[48:51], v[214:217], v[12:15]
	v_mfma_f32_16x16x32_bf16 v[8:11], v[64:67], v[214:217], v[8:11]
	v_mfma_f32_16x16x32_bf16 v[76:79], v[52:55], v[176:179], v[76:79]
	v_mfma_f32_16x16x32_bf16 v[72:75], v[68:71], v[176:179], v[72:75]
	v_mfma_f32_16x16x32_bf16 v[60:63], v[52:55], v[202:205], v[60:63]
	v_mfma_f32_16x16x32_bf16 v[56:59], v[68:71], v[202:205], v[56:59]
	v_mfma_f32_16x16x32_bf16 v[36:39], v[52:55], v[210:213], v[36:39]
	v_mfma_f32_16x16x32_bf16 v[28:31], v[68:71], v[210:213], v[28:31]
	s_waitcnt lgkmcnt(0)
	v_mfma_f32_16x16x32_bf16 v[12:15], v[52:55], v[218:221], v[12:15]
	v_mfma_f32_16x16x32_bf16 v[8:11], v[68:71], v[218:221], v[8:11]
	s_setprio 0
	s_barrier
	s_add_u32 s26, s26, 0x80080
	s_addc_u32 s27, s27, 0
	s_add_i32 s28, s28, s35
	v_lshl_add_u64 v[48:49], s[26:27], 0, v[144:145]
	s_mov_b32 m0, s28
	s_nop 0
	global_load_lds_dwordx4 v[48:49], off
	v_lshl_add_u64 v[48:49], s[26:27], 0, v[166:167]
	s_add_i32 m0, s28, 0x2000
	s_nop 0
	global_load_lds_dwordx4 v[48:49], off
	s_waitcnt vmcnt(6)
	s_barrier
	s_setprio 1
	v_mfma_f32_16x16x32_bf16 v[24:27], v[222:225], v[172:175], v[24:27]
	v_mfma_f32_16x16x32_bf16 v[68:71], v[226:229], v[176:179], v[24:27]
	v_mfma_f32_16x16x32_bf16 v[24:27], v[230:233], v[172:175], v[32:35]
	v_mfma_f32_16x16x32_bf16 v[64:67], v[234:237], v[176:179], v[24:27]
	v_mfma_f32_16x16x32_bf16 v[24:27], v[222:225], v[198:201], v[40:43]
	v_mfma_f32_16x16x32_bf16 v[52:55], v[226:229], v[202:205], v[24:27]
	v_mfma_f32_16x16x32_bf16 v[24:27], v[230:233], v[198:201], v[44:47]
	v_mfma_f32_16x16x32_bf16 v[20:23], v[222:225], v[206:209], v[20:23]
	v_mfma_f32_16x16x32_bf16 v[16:19], v[230:233], v[206:209], v[16:19]
	v_mfma_f32_16x16x32_bf16 v[4:7], v[222:225], v[214:217], v[4:7]
	v_mfma_f32_16x16x32_bf16 v[0:3], v[230:233], v[214:217], v[0:3]
	v_mfma_f32_16x16x32_bf16 v[48:51], v[234:237], v[202:205], v[24:27]
	v_mfma_f32_16x16x32_bf16 v[20:23], v[226:229], v[210:213], v[20:23]
	v_mfma_f32_16x16x32_bf16 v[16:19], v[234:237], v[210:213], v[16:19]
	v_mfma_f32_16x16x32_bf16 v[4:7], v[226:229], v[218:221], v[4:7]
	v_mfma_f32_16x16x32_bf16 v[0:3], v[234:237], v[218:221], v[0:3]
	s_setprio 0
	s_add_i32 s57, s57, 2
	s_add_u32 s6, s6, 0x100
	s_addc_u32 s7, s7, 0
	s_add_u32 s11, s11, 0x100
	s_addc_u32 s19, s19, 0
	s_cmp_gt_u32 s57, 29
	s_barrier
	s_cbranch_scc0 .LBB0_119
	s_load_dwordx2 s[6:7], s[20:21], 0x58
	v_lshl_or_b32 v172, s56, 8, v195
	v_ashrrev_i32_e32 v173, 31, v172
	s_cmp_gt_i32 s56, 7
	v_lshl_add_u32 v174, s10, 8, v193
	s_waitcnt lgkmcnt(0)
	v_lshl_add_u64 v[32:33], v[172:173], 2, s[6:7]
	global_load_dwordx4 v[40:43], v[32:33], off offset:16
	global_load_dwordx4 v[44:47], v[32:33], off
	global_load_dwordx4 v[24:27], v[32:33], off offset:528
	s_nop 0
	global_load_dwordx4 v[32:35], v[32:33], off offset:512
	s_cselect_b64 s[10:11], -1, 0
	s_lshl_b32 s6, s56, 2
	s_sub_i32 s6, s6, 32
	s_ashr_i32 s7, s6, 31
	s_or_b64 s[26:27], s[6:7], s[76:77]
	s_mov_b32 s6, 0x3e6d3388
	s_mov_b32 s28, 0xbf3a00e3
	v_ashrrev_i32_e32 v175, 31, v174
	v_lshlrev_b64 v[176:177], 13, v[174:175]
	v_lshl_add_u64 v[176:177], s[14:15], 0, v[176:177]
	v_lshl_add_u64 v[176:177], v[172:173], 1, v[176:177]
	s_cmp_lt_i32 s56, 8
	s_waitcnt vmcnt(0)
	v_pk_add_f32 v[136:137], v[136:137], v[40:41]
	v_pk_add_f32 v[140:141], v[140:141], v[44:45]
	v_pk_add_f32 v[142:143], v[142:143], v[46:47]
	v_and_b32_e32 v181, 0x7fffffff, v141
	v_and_b32_e32 v180, 0x7fffffff, v140
	v_pk_fma_f32 v[178:179], v[180:181], s[6:7], 1.0 op_sel_hi:[1,0,0]
	v_pk_mul_f32 v[202:203], v[140:141], v[140:141]
	v_rcp_f32_e32 v198, v178
	v_rcp_f32_e32 v199, v179
	v_mov_b64_e32 v[178:179], s[28:29]
	v_pk_mul_f32 v[202:203], v[202:203], s[60:61] op_sel_hi:[1,0]
	v_pk_add_f32 v[138:139], v[138:139], v[42:43]
	v_pk_fma_f32 v[200:201], v[198:199], s[92:93], v[178:179] op_sel_hi:[1,0,0]
	v_exp_f32_e32 v202, v202
	v_pk_fma_f32 v[200:201], v[198:199], v[200:201], s[96:97] op_sel_hi:[1,1,0]
	v_exp_f32_e32 v203, v203
	v_pk_fma_f32 v[200:201], v[198:199], v[200:201], s[44:45] op_sel_hi:[1,1,0]
	v_pk_add_f32 v[132:133], v[132:133], v[32:33]
	v_pk_fma_f32 v[200:201], v[198:199], v[200:201], s[58:59] op_sel_hi:[1,1,0]
	v_pk_add_f32 v[134:135], v[134:135], v[34:35]
	v_pk_mul_f32 v[198:199], v[198:199], v[200:201]
	v_pk_mul_f32 v[200:201], v[142:143], v[142:143]
	v_pk_fma_f32 v[198:199], v[202:203], v[198:199], 0.5 op_sel_hi:[1,1,0] neg_lo:[1,0,0] neg_hi:[1,0,0]
	v_pk_mul_f32 v[200:201], v[200:201], s[60:61] op_sel_hi:[1,0]
	v_pk_mul_f32 v[180:181], v[180:181], v[198:199]
	v_exp_f32_e32 v200, v200
	v_pk_fma_f32 v[140:141], v[140:141], 0.5, v[180:181] op_sel_hi:[1,0,1]
	v_and_b32_e32 v181, 0x7fffffff, v143
	v_and_b32_e32 v180, 0x7fffffff, v142
	v_pk_fma_f32 v[198:199], v[180:181], s[6:7], 1.0 op_sel_hi:[1,0,0]
	v_exp_f32_e32 v201, v201
	v_rcp_f32_e32 v198, v198
	v_rcp_f32_e32 v199, v199
	v_pk_add_f32 v[128:129], v[128:129], v[24:25]
	v_pk_add_f32 v[130:131], v[130:131], v[26:27]
	v_pk_fma_f32 v[202:203], v[198:199], s[92:93], v[178:179] op_sel_hi:[1,0,0]
	s_nop 0
	v_pk_fma_f32 v[202:203], v[198:199], v[202:203], s[96:97] op_sel_hi:[1,1,0]
	s_nop 0
	v_pk_fma_f32 v[202:203], v[198:199], v[202:203], s[44:45] op_sel_hi:[1,1,0]
	s_nop 0
	v_pk_fma_f32 v[202:203], v[198:199], v[202:203], s[58:59] op_sel_hi:[1,1,0]
	s_nop 0
	v_pk_mul_f32 v[198:199], v[198:199], v[202:203]
	v_pk_mul_f32 v[202:203], v[136:137], v[136:137]
	v_pk_fma_f32 v[198:199], v[200:201], v[198:199], 0.5 op_sel_hi:[1,1,0] neg_lo:[1,0,0] neg_hi:[1,0,0]
	v_pk_mul_f32 v[202:203], v[202:203], s[60:61] op_sel_hi:[1,0]
	v_pk_mul_f32 v[180:181], v[180:181], v[198:199]
	v_exp_f32_e32 v202, v202
	v_pk_fma_f32 v[142:143], v[142:143], 0.5, v[180:181] op_sel_hi:[1,0,1]
	v_and_b32_e32 v181, 0x7fffffff, v137
	v_and_b32_e32 v180, 0x7fffffff, v136
	v_pk_fma_f32 v[198:199], v[180:181], s[6:7], 1.0 op_sel_hi:[1,0,0]
	v_exp_f32_e32 v203, v203
	v_rcp_f32_e32 v198, v198
	v_rcp_f32_e32 v199, v199
	s_nop 0
	v_pk_fma_f32 v[200:201], v[198:199], s[92:93], v[178:179] op_sel_hi:[1,0,0]
	s_nop 0
	v_pk_fma_f32 v[200:201], v[198:199], v[200:201], s[96:97] op_sel_hi:[1,1,0]
	s_nop 0
	v_pk_fma_f32 v[200:201], v[198:199], v[200:201], s[44:45] op_sel_hi:[1,1,0]
	s_nop 0
	v_pk_fma_f32 v[200:201], v[198:199], v[200:201], s[58:59] op_sel_hi:[1,1,0]
	s_nop 0
	v_pk_mul_f32 v[198:199], v[198:199], v[200:201]
	v_pk_mul_f32 v[200:201], v[138:139], v[138:139]
	v_pk_fma_f32 v[198:199], v[202:203], v[198:199], 0.5 op_sel_hi:[1,1,0] neg_lo:[1,0,0] neg_hi:[1,0,0]
	v_pk_mul_f32 v[200:201], v[200:201], s[60:61] op_sel_hi:[1,0]
	v_pk_mul_f32 v[180:181], v[180:181], v[198:199]
	v_exp_f32_e32 v200, v200
	v_pk_fma_f32 v[136:137], v[136:137], 0.5, v[180:181] op_sel_hi:[1,0,1]
	v_and_b32_e32 v181, 0x7fffffff, v139
	v_and_b32_e32 v180, 0x7fffffff, v138
	v_pk_fma_f32 v[198:199], v[180:181], s[6:7], 1.0 op_sel_hi:[1,0,0]
	v_exp_f32_e32 v201, v201
	v_rcp_f32_e32 v198, v198
	v_rcp_f32_e32 v199, v199
	s_nop 0
	v_pk_fma_f32 v[202:203], v[198:199], s[92:93], v[178:179] op_sel_hi:[1,0,0]
	s_nop 0
	v_pk_fma_f32 v[202:203], v[198:199], v[202:203], s[96:97] op_sel_hi:[1,1,0]
	s_nop 0
	v_pk_fma_f32 v[202:203], v[198:199], v[202:203], s[44:45] op_sel_hi:[1,1,0]
	s_nop 0
	v_pk_fma_f32 v[202:203], v[198:199], v[202:203], s[58:59] op_sel_hi:[1,1,0]
	s_nop 0
	v_pk_mul_f32 v[198:199], v[198:199], v[202:203]
	v_pk_mul_f32 v[202:203], v[132:133], v[132:133]
	v_pk_fma_f32 v[198:199], v[200:201], v[198:199], 0.5 op_sel_hi:[1,1,0] neg_lo:[1,0,0] neg_hi:[1,0,0]
	v_cvt_pk_bf16_f32 v200, v136, v137
	v_pk_mul_f32 v[202:203], v[202:203], s[60:61] op_sel_hi:[1,0]
	v_pk_mul_f32 v[180:181], v[180:181], v[198:199]
	v_cvt_pk_bf16_f32 v198, v140, v141
	v_cvt_pk_bf16_f32 v199, v142, v143
	v_exp_f32_e32 v202, v202
	v_pk_fma_f32 v[138:139], v[138:139], 0.5, v[180:181] op_sel_hi:[1,0,1]
	v_and_b32_e32 v181, 0x7fffffff, v133
	v_and_b32_e32 v180, 0x7fffffff, v132
	v_cvt_pk_bf16_f32 v201, v138, v139
	global_store_dwordx4 v[176:177], v[198:201], off
	v_exp_f32_e32 v203, v203
	s_nop 0
	v_pk_fma_f32 v[198:199], v[180:181], s[6:7], 1.0 op_sel_hi:[1,0,0]
	s_nop 0
	v_rcp_f32_e32 v198, v198
	v_rcp_f32_e32 v199, v199
	s_nop 0
	v_pk_fma_f32 v[200:201], v[198:199], s[92:93], v[178:179] op_sel_hi:[1,0,0]
	s_nop 0
	v_pk_fma_f32 v[200:201], v[198:199], v[200:201], s[96:97] op_sel_hi:[1,1,0]
	s_nop 0
	v_pk_fma_f32 v[200:201], v[198:199], v[200:201], s[44:45] op_sel_hi:[1,1,0]
	s_nop 0
	v_pk_fma_f32 v[200:201], v[198:199], v[200:201], s[58:59] op_sel_hi:[1,1,0]
	s_nop 0
	v_pk_mul_f32 v[198:199], v[198:199], v[200:201]
	v_pk_mul_f32 v[200:201], v[134:135], v[134:135]
	v_pk_fma_f32 v[198:199], v[202:203], v[198:199], 0.5 op_sel_hi:[1,1,0] neg_lo:[1,0,0] neg_hi:[1,0,0]
	v_pk_mul_f32 v[200:201], v[200:201], s[60:61] op_sel_hi:[1,0]
	v_pk_mul_f32 v[180:181], v[180:181], v[198:199]
	v_exp_f32_e32 v200, v200
	v_pk_fma_f32 v[132:133], v[132:133], 0.5, v[180:181] op_sel_hi:[1,0,1]
	v_and_b32_e32 v181, 0x7fffffff, v135
	v_and_b32_e32 v180, 0x7fffffff, v134
	v_pk_fma_f32 v[198:199], v[180:181], s[6:7], 1.0 op_sel_hi:[1,0,0]
	v_exp_f32_e32 v201, v201
	v_rcp_f32_e32 v198, v198
	v_rcp_f32_e32 v199, v199
	s_nop 0
	v_pk_fma_f32 v[202:203], v[198:199], s[92:93], v[178:179] op_sel_hi:[1,0,0]
	s_nop 0
	v_pk_fma_f32 v[202:203], v[198:199], v[202:203], s[96:97] op_sel_hi:[1,1,0]
	s_nop 0
	v_pk_fma_f32 v[202:203], v[198:199], v[202:203], s[44:45] op_sel_hi:[1,1,0]
	s_nop 0
	v_pk_fma_f32 v[202:203], v[198:199], v[202:203], s[58:59] op_sel_hi:[1,1,0]
	s_nop 0
	v_pk_mul_f32 v[198:199], v[198:199], v[202:203]
	v_pk_mul_f32 v[202:203], v[128:129], v[128:129]
	v_pk_fma_f32 v[198:199], v[200:201], v[198:199], 0.5 op_sel_hi:[1,1,0] neg_lo:[1,0,0] neg_hi:[1,0,0]
	v_pk_mul_f32 v[202:203], v[202:203], s[60:61] op_sel_hi:[1,0]
	v_pk_mul_f32 v[180:181], v[180:181], v[198:199]
	v_exp_f32_e32 v202, v202
	v_pk_fma_f32 v[134:135], v[134:135], 0.5, v[180:181] op_sel_hi:[1,0,1]
	v_and_b32_e32 v181, 0x7fffffff, v129
	v_and_b32_e32 v180, 0x7fffffff, v128
	v_pk_fma_f32 v[198:199], v[180:181], s[6:7], 1.0 op_sel_hi:[1,0,0]
	v_exp_f32_e32 v203, v203
	v_rcp_f32_e32 v198, v198
	v_rcp_f32_e32 v199, v199
	s_nop 0
	v_pk_fma_f32 v[200:201], v[198:199], s[92:93], v[178:179] op_sel_hi:[1,0,0]
	s_nop 0
	v_pk_fma_f32 v[200:201], v[198:199], v[200:201], s[96:97] op_sel_hi:[1,1,0]
	s_nop 0
	v_pk_fma_f32 v[200:201], v[198:199], v[200:201], s[44:45] op_sel_hi:[1,1,0]
	s_nop 0
	v_pk_fma_f32 v[200:201], v[198:199], v[200:201], s[58:59] op_sel_hi:[1,1,0]
	s_nop 0
	v_pk_mul_f32 v[198:199], v[198:199], v[200:201]
	v_pk_mul_f32 v[200:201], v[130:131], v[130:131]
	v_pk_fma_f32 v[198:199], v[202:203], v[198:199], 0.5 op_sel_hi:[1,1,0] neg_lo:[1,0,0] neg_hi:[1,0,0]
	s_nop 0
	v_pk_mul_f32 v[180:181], v[180:181], v[198:199]
	s_nop 0
	v_pk_fma_f32 v[128:129], v[128:129], 0.5, v[180:181] op_sel_hi:[1,0,1]
	v_and_b32_e32 v181, 0x7fffffff, v131
	v_and_b32_e32 v180, 0x7fffffff, v130
	v_pk_fma_f32 v[198:199], v[180:181], s[6:7], 1.0 op_sel_hi:[1,0,0]
	s_nop 0
	v_rcp_f32_e32 v198, v198
	v_rcp_f32_e32 v199, v199
	s_nop 0
	v_pk_fma_f32 v[178:179], v[198:199], s[92:93], v[178:179] op_sel_hi:[1,0,0]
	s_nop 0
	v_pk_fma_f32 v[178:179], v[198:199], v[178:179], s[96:97] op_sel_hi:[1,1,0]
	s_nop 0
	v_pk_fma_f32 v[178:179], v[198:199], v[178:179], s[44:45] op_sel_hi:[1,1,0]
	s_nop 0
	v_pk_fma_f32 v[178:179], v[198:199], v[178:179], s[58:59] op_sel_hi:[1,1,0]
	s_nop 0
	v_pk_mul_f32 v[178:179], v[198:199], v[178:179]
	v_pk_mul_f32 v[198:199], v[200:201], s[60:61] op_sel_hi:[1,0]
	s_nop 0
	v_exp_f32_e32 v198, v198
	v_exp_f32_e32 v199, v199
	s_nop 0
	v_pk_fma_f32 v[178:179], v[198:199], v[178:179], 0.5 op_sel_hi:[1,1,0] neg_lo:[1,0,0] neg_hi:[1,0,0]
	s_nop 0
	v_pk_mul_f32 v[178:179], v[180:181], v[178:179]
	v_cvt_pk_bf16_f32 v180, v128, v129
	s_nop 0
	v_pk_fma_f32 v[130:131], v[130:131], 0.5, v[178:179] op_sel_hi:[1,0,1]
	v_cvt_pk_bf16_f32 v178, v132, v133
	v_cvt_pk_bf16_f32 v179, v134, v135
	s_nop 0
	v_cvt_pk_bf16_f32 v181, v130, v131
	global_store_dwordx4 v[176:177], v[178:181], off offset:256
	s_cbranch_scc1 .LBB0_124
	v_pk_mul_f32 v[202:203], v[134:135], v[134:135]
	v_mov_b32_e32 v206, v132
	v_mov_b32_e32 v207, v134
	v_mov_b32_e32 v134, v133
	v_mov_b32_e32 v180, v141
	v_mov_b32_e32 v181, v143
	v_pk_mul_f32 v[200:201], v[132:133], v[132:133]
	v_pk_add_f32 v[132:133], v[206:207], v[134:135]
	v_mov_b32_e32 v178, v140
	v_mov_b32_e32 v179, v142
	v_pk_mul_f32 v[180:181], v[180:181], v[180:181]
	v_pk_add_f32 v[132:133], v[132:133], v[132:133] op_sel:[0,1] op_sel_hi:[1,0]
	v_pk_fma_f32 v[178:179], v[178:179], v[178:179], v[180:181]
	v_pk_mul_f32 v[204:205], v[128:129], v[128:129]
	v_pk_add_f32 v[140:141], v[140:141], v[140:141] op_sel:[0,1] op_sel_hi:[1,0]
	v_pk_add_f32 v[142:143], v[142:143], v[142:143] op_sel:[0,1] op_sel_hi:[1,0]
	v_pk_add_f32 v[128:129], v[128:129], v[128:129] op_sel:[0,1] op_sel_hi:[1,0]
	v_and_b32_e32 v133, 64, v189
	v_pk_add_f32 v[178:179], v[178:179], v[178:179] op_sel_hi:[0,1]
	v_xor_b32_e32 v129, 16, v189
	v_add_u32_e32 v197, 64, v133
	v_mov_b32_e32 v141, v200
	v_mov_b32_e32 v143, v201
	v_pk_mul_f32 v[176:177], v[138:139], v[138:139]
	v_mul_f32_e32 v178, v136, v136
	v_cmp_lt_i32_e32 vcc, v129, v197
	v_mov_b32_e32 v134, v138
	v_mov_b32_e32 v135, v204
	v_mov_b32_e32 v204, v139
	v_pk_add_f32 v[138:139], v[140:141], v[142:143]
	v_mov_b32_e32 v140, v136
	v_mov_b32_e32 v141, v202
	v_mov_b32_e32 v202, v137
	v_pk_fma_f32 v[180:181], v[136:137], v[136:137], v[178:179] op_sel_hi:[1,1,0]
	v_mul_f32_e32 v178, v130, v130
	v_cndmask_b32_e32 v129, v189, v129, vcc
	v_pk_add_f32 v[136:137], v[140:141], v[202:203]
	v_pk_fma_f32 v[198:199], v[130:131], v[130:131], v[178:179] op_sel_hi:[1,1,0]
	v_lshlrev_b32_e32 v206, 2, v129
	v_pk_add_f32 v[134:135], v[134:135], v[204:205]
	v_pk_add_f32 v[136:137], v[138:139], v[136:137]
	v_mov_b32_e32 v178, v130
	v_mov_b32_e32 v180, v131
	v_mov_b32_e32 v133, v176
	v_mov_b32_e32 v129, v177
	v_pk_add_f32 v[134:135], v[136:137], v[134:135]
	v_mov_b32_e32 v198, v145
	v_pk_add_f32 v[130:131], v[178:179], v[180:181]
	v_pk_add_f32 v[128:129], v[132:133], v[128:129]
	v_pk_add_f32 v[134:135], v[134:135], v[198:199]
	v_pk_add_f32 v[128:129], v[128:129], v[130:131]
	v_xor_b32_e32 v132, 32, v189
	v_pk_add_f32 v[128:129], v[128:129], v[134:135]
	ds_bpermute_b32 v130, v206, v128
	ds_bpermute_b32 v131, v206, v129
	v_cmp_lt_i32_e32 vcc, v132, v197
	s_waitcnt lgkmcnt(0)
	v_pk_add_f32 v[128:129], v[128:129], v[130:131]
	v_cndmask_b32_e32 v132, v189, v132, vcc
	v_lshlrev_b32_e32 v132, 2, v132
	ds_bpermute_b32 v130, v132, v128
	ds_bpermute_b32 v131, v132, v129
	s_and_saveexec_b64 s[6:7], s[0:1]
	s_cbranch_execz .LBB0_123
	v_lshlrev_b64 v[132:133], 8, v[174:175]
	s_waitcnt lgkmcnt(0)
	v_pk_add_f32 v[128:129], v[128:129], v[130:131]
	v_lshl_add_u64 v[130:131], s[16:17], 0, v[132:133]
	v_lshl_add_u64 v[130:131], s[26:27], 3, v[130:131]
	global_store_dwordx2 v[130:131], v[128:129], off

.LBB0_700:
	s_add_u32 s28, s26, 0xfff80080
	s_addc_u32 s29, s27, -1
	s_add_i32 s71, 0, 0x10000
	v_add_u32_e32 v172, s71, v143
	ds_read_b128 v[138:141], v172
	ds_read_b128 v[164:167], v172 offset:1024
	ds_read_b128 v[168:171], v172 offset:2048
	ds_read_b128 v[172:175], v172 offset:3072
	s_cmp_eq_u32 s70, 28
	s_cselect_b32 s31, s7, s29
	s_cselect_b32 s30, s6, s28
	s_cselect_b32 s29, s9, s67
	s_cselect_b32 s28, s8, s21
	v_lshl_add_u64 v[180:181], s[26:27], 0, v[134:135]
	s_add_i32 m0, s51, 0xc000
	ds_read_b128 v[176:179], v163
	ds_read_b128 v[198:201], v163 offset:2048
	ds_read_b128 v[206:209], v163 offset:4096
	ds_read_b128 v[214:217], v163 offset:6144
	global_load_lds_dwordx4 v[180:181], off
	v_lshl_add_u64 v[180:181], s[26:27], 0, v[136:137]
	s_add_i32 m0, s51, 0xe000
	s_nop 0
	global_load_lds_dwordx4 v[180:181], off
	s_waitcnt lgkmcnt(4)
	s_barrier
	s_setprio 1
	ds_read_b128 v[194:197], v163 offset:1024
	ds_read_b128 v[202:205], v163 offset:3072
	ds_read_b128 v[210:213], v163 offset:5120
	ds_read_b128 v[218:221], v163 offset:7168
	s_waitcnt lgkmcnt(7)
	v_mfma_f32_16x16x32_bf16 v[124:127], v[138:141], v[176:179], v[124:127]
	v_mfma_f32_16x16x32_bf16 v[116:119], v[168:171], v[176:179], v[116:119]
	s_waitcnt lgkmcnt(6)
	v_mfma_f32_16x16x32_bf16 v[108:111], v[138:141], v[198:201], v[108:111]
	v_mfma_f32_16x16x32_bf16 v[100:103], v[168:171], v[198:201], v[100:103]
	s_waitcnt lgkmcnt(5)
	v_mfma_f32_16x16x32_bf16 v[92:95], v[138:141], v[206:209], v[92:95]
	v_mfma_f32_16x16x32_bf16 v[84:87], v[168:171], v[206:209], v[84:87]
	s_waitcnt lgkmcnt(4)
	v_mfma_f32_16x16x32_bf16 v[76:79], v[138:141], v[214:217], v[76:79]
	v_mfma_f32_16x16x32_bf16 v[68:71], v[168:171], v[214:217], v[68:71]
	s_waitcnt lgkmcnt(3)
	v_mfma_f32_16x16x32_bf16 v[124:127], v[164:167], v[194:197], v[124:127]
	v_mfma_f32_16x16x32_bf16 v[116:119], v[172:175], v[194:197], v[116:119]
	s_waitcnt lgkmcnt(2)
	v_mfma_f32_16x16x32_bf16 v[108:111], v[164:167], v[202:205], v[108:111]
	v_mfma_f32_16x16x32_bf16 v[100:103], v[172:175], v[202:205], v[100:103]
	s_waitcnt lgkmcnt(1)
	v_mfma_f32_16x16x32_bf16 v[92:95], v[164:167], v[210:213], v[92:95]
	v_mfma_f32_16x16x32_bf16 v[84:87], v[172:175], v[210:213], v[84:87]
	s_waitcnt lgkmcnt(0)
	v_mfma_f32_16x16x32_bf16 v[76:79], v[164:167], v[218:221], v[76:79]
	v_mfma_f32_16x16x32_bf16 v[68:71], v[172:175], v[218:221], v[68:71]
	s_setprio 0
	s_barrier
	s_add_i32 s74, 0, 0x14000
	v_add_u32_e32 v180, s74, v143
	s_add_i32 s71, s71, s50
	ds_read_b128 v[222:225], v180
	ds_read_b128 v[226:229], v180 offset:1024
	ds_read_b128 v[230:233], v180 offset:2048
	ds_read_b128 v[234:237], v180 offset:3072
	v_lshl_add_u64 v[180:181], s[28:29], 0, v[144:145]
	s_mov_b32 m0, s71
	v_lshl_add_u64 v[238:239], s[28:29], 0, v[128:129]
	global_load_lds_dwordx4 v[180:181], off
	s_add_i32 m0, s71, 0x2000
	s_nop 0
	global_load_lds_dwordx4 v[238:239], off
	s_barrier
	s_setprio 1
	s_waitcnt lgkmcnt(3)
	v_mfma_f32_16x16x32_bf16 v[120:123], v[222:225], v[176:179], v[120:123]
	s_waitcnt lgkmcnt(1)
	v_mfma_f32_16x16x32_bf16 v[112:115], v[230:233], v[176:179], v[112:115]
	v_mfma_f32_16x16x32_bf16 v[104:107], v[222:225], v[198:201], v[104:107]
	v_mfma_f32_16x16x32_bf16 v[96:99], v[230:233], v[198:201], v[96:99]
	v_mfma_f32_16x16x32_bf16 v[88:91], v[222:225], v[206:209], v[88:91]
	v_mfma_f32_16x16x32_bf16 v[80:83], v[230:233], v[206:209], v[80:83]
	v_mfma_f32_16x16x32_bf16 v[72:75], v[222:225], v[214:217], v[72:75]
	v_mfma_f32_16x16x32_bf16 v[64:67], v[230:233], v[214:217], v[64:67]
	v_mfma_f32_16x16x32_bf16 v[120:123], v[226:229], v[194:197], v[120:123]
	s_waitcnt lgkmcnt(0)
	v_mfma_f32_16x16x32_bf16 v[112:115], v[234:237], v[194:197], v[112:115]
	v_mfma_f32_16x16x32_bf16 v[104:107], v[226:229], v[202:205], v[104:107]
	v_mfma_f32_16x16x32_bf16 v[96:99], v[234:237], v[202:205], v[96:99]
	v_mfma_f32_16x16x32_bf16 v[88:91], v[226:229], v[210:213], v[88:91]
	v_mfma_f32_16x16x32_bf16 v[80:83], v[234:237], v[210:213], v[80:83]
	v_mfma_f32_16x16x32_bf16 v[72:75], v[226:229], v[218:221], v[72:75]
	v_mfma_f32_16x16x32_bf16 v[64:67], v[234:237], v[218:221], v[64:67]
	s_setprio 0
	s_mov_b32 m0, s51
	v_lshl_add_u64 v[240:241], s[30:31], 0, v[132:133]
	s_barrier
	ds_read_b128 v[176:179], v163 offset:16384
	ds_read_b128 v[194:197], v163 offset:17408
	ds_read_b128 v[198:201], v163 offset:18432
	ds_read_b128 v[202:205], v163 offset:19456
	ds_read_b128 v[206:209], v163 offset:20480
	ds_read_b128 v[210:213], v163 offset:21504
	ds_read_b128 v[214:217], v163 offset:22528
	ds_read_b128 v[218:221], v163 offset:23552
	global_load_lds_dwordx4 v[240:241], off
	v_lshl_add_u64 v[242:243], s[30:31], 0, v[130:131]
	s_mov_b32 m0, s52
	s_nop 0
	global_load_lds_dwordx4 v[242:243], off
	s_barrier
	s_setprio 1
	s_waitcnt lgkmcnt(7)
	v_mfma_f32_16x16x32_bf16 v[60:63], v[138:141], v[176:179], v[60:63]
	v_mfma_f32_16x16x32_bf16 v[52:55], v[168:171], v[176:179], v[52:55]
	s_waitcnt lgkmcnt(5)
	v_mfma_f32_16x16x32_bf16 v[44:47], v[138:141], v[198:201], v[44:47]
	v_mfma_f32_16x16x32_bf16 v[36:39], v[168:171], v[198:201], v[36:39]
	s_waitcnt lgkmcnt(3)
	v_mfma_f32_16x16x32_bf16 v[28:31], v[138:141], v[206:209], v[28:31]
	v_mfma_f32_16x16x32_bf16 v[20:23], v[168:171], v[206:209], v[20:23]
	s_waitcnt lgkmcnt(1)
	v_mfma_f32_16x16x32_bf16 v[12:15], v[138:141], v[214:217], v[12:15]
	v_mfma_f32_16x16x32_bf16 v[4:7], v[168:171], v[214:217], v[4:7]
	v_mfma_f32_16x16x32_bf16 v[60:63], v[164:167], v[194:197], v[60:63]
	v_mfma_f32_16x16x32_bf16 v[52:55], v[172:175], v[194:197], v[52:55]
	v_mfma_f32_16x16x32_bf16 v[44:47], v[164:167], v[202:205], v[44:47]
	v_mfma_f32_16x16x32_bf16 v[36:39], v[172:175], v[202:205], v[36:39]
	v_mfma_f32_16x16x32_bf16 v[28:31], v[164:167], v[210:213], v[28:31]
	v_mfma_f32_16x16x32_bf16 v[20:23], v[172:175], v[210:213], v[20:23]
	s_waitcnt lgkmcnt(0)
	v_mfma_f32_16x16x32_bf16 v[12:15], v[164:167], v[218:221], v[12:15]
	v_mfma_f32_16x16x32_bf16 v[4:7], v[172:175], v[218:221], v[4:7]
	s_setprio 0
	s_barrier
	s_add_u32 s72, s28, 0x80000
	s_addc_u32 s73, s29, 0
	s_add_i32 s71, s74, s50
	v_lshl_add_u64 v[138:139], s[72:73], 0, v[144:145]
	s_mov_b32 m0, s71
	s_nop 0
	global_load_lds_dwordx4 v[138:139], off
	v_lshl_add_u64 v[138:139], s[72:73], 0, v[128:129]
	s_add_i32 m0, s71, 0x2000
	s_nop 0
	global_load_lds_dwordx4 v[138:139], off
	s_waitcnt vmcnt(6)
	s_barrier
	s_setprio 1
	v_mfma_f32_16x16x32_bf16 v[56:59], v[222:225], v[176:179], v[56:59]
	v_mfma_f32_16x16x32_bf16 v[48:51], v[230:233], v[176:179], v[48:51]
	v_mfma_f32_16x16x32_bf16 v[40:43], v[222:225], v[198:201], v[40:43]
	v_mfma_f32_16x16x32_bf16 v[32:35], v[230:233], v[198:201], v[32:35]
	v_mfma_f32_16x16x32_bf16 v[24:27], v[222:225], v[206:209], v[24:27]
	v_mfma_f32_16x16x32_bf16 v[16:19], v[230:233], v[206:209], v[16:19]
	v_mfma_f32_16x16x32_bf16 v[8:11], v[222:225], v[214:217], v[8:11]
	v_mfma_f32_16x16x32_bf16 v[0:3], v[230:233], v[214:217], v[0:3]
	v_mfma_f32_16x16x32_bf16 v[56:59], v[226:229], v[194:197], v[56:59]
	v_mfma_f32_16x16x32_bf16 v[48:51], v[234:237], v[194:197], v[48:51]
	v_mfma_f32_16x16x32_bf16 v[40:43], v[226:229], v[202:205], v[40:43]
	v_mfma_f32_16x16x32_bf16 v[32:35], v[234:237], v[202:205], v[32:35]
	v_mfma_f32_16x16x32_bf16 v[24:27], v[226:229], v[210:213], v[24:27]
	v_mfma_f32_16x16x32_bf16 v[16:19], v[234:237], v[210:213], v[16:19]
	v_mfma_f32_16x16x32_bf16 v[8:11], v[226:229], v[218:221], v[8:11]
	v_mfma_f32_16x16x32_bf16 v[0:3], v[234:237], v[218:221], v[0:3]
	s_setprio 0
	s_add_i32 s71, 0, 0x18000
	v_add_u32_e32 v172, s71, v143
	s_barrier
	ds_read_b128 v[138:141], v172
	ds_read_b128 v[164:167], v172 offset:1024
	ds_read_b128 v[168:171], v172 offset:2048
	ds_read_b128 v[172:175], v172 offset:3072
	s_add_u32 s30, s30, 0x80000
	s_addc_u32 s31, s31, 0
	s_mov_b32 m0, s53
	v_lshl_add_u64 v[222:223], s[30:31], 0, v[132:133]
	ds_read_b128 v[176:179], v163 offset:32768
	ds_read_b128 v[198:201], v163 offset:34816
	ds_read_b128 v[206:209], v163 offset:36864
	ds_read_b128 v[214:217], v163 offset:38912
	global_load_lds_dwordx4 v[222:223], off
	v_lshl_add_u64 v[222:223], s[30:31], 0, v[130:131]
	s_mov_b32 m0, s54
	s_nop 0
	global_load_lds_dwordx4 v[222:223], off
	s_waitcnt lgkmcnt(4)
	s_barrier
	s_setprio 1
	ds_read_b128 v[194:197], v163 offset:33792
	ds_read_b128 v[202:205], v163 offset:35840
	ds_read_b128 v[210:213], v163 offset:37888
	ds_read_b128 v[218:221], v163 offset:39936
	s_waitcnt lgkmcnt(7)
	v_mfma_f32_16x16x32_bf16 v[124:127], v[138:141], v[176:179], v[124:127]
	v_mfma_f32_16x16x32_bf16 v[116:119], v[168:171], v[176:179], v[116:119]
	s_waitcnt lgkmcnt(6)
	v_mfma_f32_16x16x32_bf16 v[108:111], v[138:141], v[198:201], v[108:111]
	v_mfma_f32_16x16x32_bf16 v[100:103], v[168:171], v[198:201], v[100:103]
	s_waitcnt lgkmcnt(5)
	v_mfma_f32_16x16x32_bf16 v[92:95], v[138:141], v[206:209], v[92:95]
	v_mfma_f32_16x16x32_bf16 v[84:87], v[168:171], v[206:209], v[84:87]
	s_waitcnt lgkmcnt(4)
	v_mfma_f32_16x16x32_bf16 v[76:79], v[138:141], v[214:217], v[76:79]
	v_mfma_f32_16x16x32_bf16 v[68:71], v[168:171], v[214:217], v[68:71]
	s_waitcnt lgkmcnt(3)
	v_mfma_f32_16x16x32_bf16 v[124:127], v[164:167], v[194:197], v[124:127]
	v_mfma_f32_16x16x32_bf16 v[116:119], v[172:175], v[194:197], v[116:119]
	s_waitcnt lgkmcnt(2)
	v_mfma_f32_16x16x32_bf16 v[108:111], v[164:167], v[202:205], v[108:111]
	v_mfma_f32_16x16x32_bf16 v[100:103], v[172:175], v[202:205], v[100:103]
	s_waitcnt lgkmcnt(1)
	v_mfma_f32_16x16x32_bf16 v[92:95], v[164:167], v[210:213], v[92:95]
	v_mfma_f32_16x16x32_bf16 v[84:87], v[172:175], v[210:213], v[84:87]
	s_waitcnt lgkmcnt(0)
	v_mfma_f32_16x16x32_bf16 v[76:79], v[164:167], v[218:221], v[76:79]
	v_mfma_f32_16x16x32_bf16 v[68:71], v[172:175], v[218:221], v[68:71]
	s_setprio 0
	s_barrier
	s_add_i32 s30, 0, 0x1c000
	s_add_i32 s31, s71, s50
	v_add_u32_e32 v193, s30, v143
	v_lshl_add_u64 v[180:181], v[180:181], 0, s[86:87]
	s_mov_b32 m0, s31
	ds_read_b128 v[222:225], v193
	ds_read_b128 v[226:229], v193 offset:1024
	ds_read_b128 v[230:233], v193 offset:2048
	ds_read_b128 v[234:237], v193 offset:3072
	global_load_lds_dwordx4 v[180:181], off
	v_lshl_add_u64 v[180:181], v[238:239], 0, s[86:87]
	s_add_i32 m0, s31, 0x2000
	s_nop 0
	global_load_lds_dwordx4 v[180:181], off
	s_barrier
	s_setprio 1
	s_waitcnt lgkmcnt(3)
	v_mfma_f32_16x16x32_bf16 v[120:123], v[222:225], v[176:179], v[120:123]
	s_waitcnt lgkmcnt(1)
	v_mfma_f32_16x16x32_bf16 v[112:115], v[230:233], v[176:179], v[112:115]
	v_mfma_f32_16x16x32_bf16 v[104:107], v[222:225], v[198:201], v[104:107]
	v_mfma_f32_16x16x32_bf16 v[96:99], v[230:233], v[198:201], v[96:99]
	v_mfma_f32_16x16x32_bf16 v[88:91], v[222:225], v[206:209], v[88:91]
	v_mfma_f32_16x16x32_bf16 v[80:83], v[230:233], v[206:209], v[80:83]
	v_mfma_f32_16x16x32_bf16 v[72:75], v[222:225], v[214:217], v[72:75]
	v_mfma_f32_16x16x32_bf16 v[64:67], v[230:233], v[214:217], v[64:67]
	v_mfma_f32_16x16x32_bf16 v[120:123], v[226:229], v[194:197], v[120:123]
	s_waitcnt lgkmcnt(0)
	v_mfma_f32_16x16x32_bf16 v[112:115], v[234:237], v[194:197], v[112:115]
	v_mfma_f32_16x16x32_bf16 v[104:107], v[226:229], v[202:205], v[104:107]
	v_mfma_f32_16x16x32_bf16 v[96:99], v[234:237], v[202:205], v[96:99]
	v_mfma_f32_16x16x32_bf16 v[88:91], v[226:229], v[210:213], v[88:91]
	v_mfma_f32_16x16x32_bf16 v[80:83], v[234:237], v[210:213], v[80:83]
	v_mfma_f32_16x16x32_bf16 v[72:75], v[226:229], v[218:221], v[72:75]
	v_mfma_f32_16x16x32_bf16 v[64:67], v[234:237], v[218:221], v[64:67]
	s_setprio 0
	s_mov_b32 m0, s12
	v_lshl_add_u64 v[180:181], v[240:241], 0, s[86:87]
	s_barrier
	ds_read_b128 v[176:179], v163 offset:49152
	ds_read_b128 v[194:197], v163 offset:50176
	ds_read_b128 v[198:201], v163 offset:51200
	ds_read_b128 v[202:205], v163 offset:52224
	ds_read_b128 v[206:209], v163 offset:53248
	ds_read_b128 v[210:213], v163 offset:54272
	ds_read_b128 v[214:217], v163 offset:55296
	ds_read_b128 v[218:221], v163 offset:56320
	global_load_lds_dwordx4 v[180:181], off
	v_lshl_add_u64 v[180:181], v[242:243], 0, s[86:87]
	s_mov_b32 m0, s13
	s_nop 0
	global_load_lds_dwordx4 v[180:181], off
	s_barrier
	s_setprio 1
	s_waitcnt lgkmcnt(7)
	v_mfma_f32_16x16x32_bf16 v[60:63], v[138:141], v[176:179], v[60:63]
	v_mfma_f32_16x16x32_bf16 v[52:55], v[168:171], v[176:179], v[52:55]
	s_waitcnt lgkmcnt(5)
	v_mfma_f32_16x16x32_bf16 v[44:47], v[138:141], v[198:201], v[44:47]
	v_mfma_f32_16x16x32_bf16 v[36:39], v[168:171], v[198:201], v[36:39]
	s_waitcnt lgkmcnt(3)
	v_mfma_f32_16x16x32_bf16 v[28:31], v[138:141], v[206:209], v[28:31]
	v_mfma_f32_16x16x32_bf16 v[20:23], v[168:171], v[206:209], v[20:23]
	s_waitcnt lgkmcnt(1)
	v_mfma_f32_16x16x32_bf16 v[12:15], v[138:141], v[214:217], v[12:15]
	v_mfma_f32_16x16x32_bf16 v[4:7], v[168:171], v[214:217], v[4:7]
	v_mfma_f32_16x16x32_bf16 v[60:63], v[164:167], v[194:197], v[60:63]
	v_mfma_f32_16x16x32_bf16 v[52:55], v[172:175], v[194:197], v[52:55]
	v_mfma_f32_16x16x32_bf16 v[44:47], v[164:167], v[202:205], v[44:47]
	v_mfma_f32_16x16x32_bf16 v[36:39], v[172:175], v[202:205], v[36:39]
	v_mfma_f32_16x16x32_bf16 v[28:31], v[164:167], v[210:213], v[28:31]
	v_mfma_f32_16x16x32_bf16 v[20:23], v[172:175], v[210:213], v[20:23]
	s_waitcnt lgkmcnt(0)
	v_mfma_f32_16x16x32_bf16 v[12:15], v[164:167], v[218:221], v[12:15]
	v_mfma_f32_16x16x32_bf16 v[4:7], v[172:175], v[218:221], v[4:7]
	s_setprio 0
	s_barrier
	s_add_u32 s28, s28, 0x80080
	s_addc_u32 s29, s29, 0
	s_add_i32 s30, s30, s50
	v_lshl_add_u64 v[138:139], s[28:29], 0, v[144:145]
	s_mov_b32 m0, s30
	s_nop 0
	global_load_lds_dwordx4 v[138:139], off
	v_lshl_add_u64 v[138:139], s[28:29], 0, v[128:129]
	s_add_i32 m0, s30, 0x2000
	s_nop 0
	global_load_lds_dwordx4 v[138:139], off
	s_waitcnt vmcnt(6)
	s_barrier
	s_setprio 1
	v_mfma_f32_16x16x32_bf16 v[56:59], v[222:225], v[176:179], v[56:59]
	v_mfma_f32_16x16x32_bf16 v[48:51], v[230:233], v[176:179], v[48:51]
	v_mfma_f32_16x16x32_bf16 v[40:43], v[222:225], v[198:201], v[40:43]
	v_mfma_f32_16x16x32_bf16 v[32:35], v[230:233], v[198:201], v[32:35]
	v_mfma_f32_16x16x32_bf16 v[24:27], v[222:225], v[206:209], v[24:27]
	v_mfma_f32_16x16x32_bf16 v[16:19], v[230:233], v[206:209], v[16:19]
	v_mfma_f32_16x16x32_bf16 v[8:11], v[222:225], v[214:217], v[8:11]
	v_mfma_f32_16x16x32_bf16 v[0:3], v[230:233], v[214:217], v[0:3]
	v_mfma_f32_16x16x32_bf16 v[56:59], v[226:229], v[194:197], v[56:59]
	v_mfma_f32_16x16x32_bf16 v[48:51], v[234:237], v[194:197], v[48:51]
	v_mfma_f32_16x16x32_bf16 v[40:43], v[226:229], v[202:205], v[40:43]
	v_mfma_f32_16x16x32_bf16 v[32:35], v[234:237], v[202:205], v[32:35]
	v_mfma_f32_16x16x32_bf16 v[24:27], v[226:229], v[210:213], v[24:27]
	v_mfma_f32_16x16x32_bf16 v[16:19], v[234:237], v[210:213], v[16:19]
	v_mfma_f32_16x16x32_bf16 v[8:11], v[226:229], v[218:221], v[8:11]
	v_mfma_f32_16x16x32_bf16 v[0:3], v[234:237], v[218:221], v[0:3]
	s_setprio 0
	s_add_i32 s70, s70, 2
	s_add_u32 s26, s26, 0x100
	s_addc_u32 s27, s27, 0
	s_add_u32 s21, s21, 0x100
	s_addc_u32 s67, s67, 0
	s_cmp_gt_u32 s70, 29
	s_barrier
	s_cbranch_scc0 .LBB0_700
	v_pk_mul_f32 v[168:169], v[126:127], s[48:49] op_sel_hi:[1,0]
	v_pk_mul_f32 v[170:171], v[124:125], s[48:49] op_sel_hi:[1,0]
	v_exp_f32_e32 v168, v168
	v_exp_f32_e32 v170, v170
	v_exp_f32_e32 v171, v171
	v_exp_f32_e32 v169, v169
	v_pk_mul_f32 v[122:123], v[126:127], v[122:123]
	v_pk_mul_f32 v[120:121], v[124:125], v[120:121]
	v_pk_add_f32 v[170:171], v[170:171], 1.0 op_sel_hi:[1,0]
	v_pk_add_f32 v[168:169], v[168:169], 1.0 op_sel_hi:[1,0]
	v_rcp_f32_e32 v124, v170
	v_rcp_f32_e32 v125, v171
	v_rcp_f32_e32 v126, v168
	v_rcp_f32_e32 v127, v169
	v_pk_mul_f32 v[114:115], v[118:119], v[114:115]
	v_pk_mul_f32 v[120:121], v[124:125], v[120:121]
	v_pk_mul_f32 v[124:125], v[118:119], s[48:49] op_sel_hi:[1,0]
	v_pk_mul_f32 v[122:123], v[126:127], v[122:123]
	v_pk_mul_f32 v[126:127], v[116:117], s[48:49] op_sel_hi:[1,0]
	v_exp_f32_e32 v124, v124
	v_exp_f32_e32 v126, v126
	v_exp_f32_e32 v127, v127
	v_exp_f32_e32 v125, v125
	v_pk_mul_f32 v[112:113], v[116:117], v[112:113]
	v_lshl_or_b32 v140, s57, 7, v162
	v_pk_add_f32 v[126:127], v[126:127], 1.0 op_sel_hi:[1,0]
	v_pk_add_f32 v[124:125], v[124:125], 1.0 op_sel_hi:[1,0]
	v_rcp_f32_e32 v116, v126
	v_rcp_f32_e32 v117, v127
	v_rcp_f32_e32 v118, v124
	v_rcp_f32_e32 v119, v125
	v_lshl_add_u32 v164, s66, 8, v142
	v_ashrrev_i32_e32 v141, 31, v140
	v_mov_b64_e32 v[138:139], s[10:11]
	v_mad_i64_i32 v[166:167], s[26:27], v164, s90, v[138:139]
	v_lshlrev_b64 v[140:141], 1, v[140:141]
	v_pk_mul_f32 v[118:119], v[118:119], v[114:115]
	v_pk_mul_f32 v[114:115], v[116:117], v[112:113]
	v_lshl_add_u64 v[166:167], v[166:167], 0, v[140:141]
	v_cvt_pk_bf16_f32 v114, v114, v115
	v_cvt_pk_bf16_f32 v115, v118, v119
	v_cvt_pk_bf16_f32 v112, v120, v121
	v_cvt_pk_bf16_f32 v113, v122, v123
	global_store_dwordx4 v[166:167], v[112:115], off
	v_pk_mul_f32 v[116:117], v[108:109], s[48:49] op_sel_hi:[1,0]
	v_pk_mul_f32 v[106:107], v[110:111], v[106:107]
	v_pk_mul_f32 v[114:115], v[110:111], s[48:49] op_sel_hi:[1,0]
	v_exp_f32_e32 v116, v116
	v_exp_f32_e32 v117, v117
	v_exp_f32_e32 v114, v114
	v_exp_f32_e32 v115, v115
	v_pk_mul_f32 v[104:105], v[108:109], v[104:105]
	v_pk_add_f32 v[116:117], v[116:117], 1.0 op_sel_hi:[1,0]
	v_pk_mul_f32 v[98:99], v[102:103], v[98:99]
	v_pk_add_f32 v[114:115], v[114:115], 1.0 op_sel_hi:[1,0]
	v_rcp_f32_e32 v108, v116
	v_rcp_f32_e32 v109, v117
	v_rcp_f32_e32 v110, v114
	v_rcp_f32_e32 v111, v115
	v_pk_mul_f32 v[96:97], v[100:101], v[96:97]
	v_pk_mul_f32 v[104:105], v[108:109], v[104:105]
	v_pk_mul_f32 v[108:109], v[102:103], s[48:49] op_sel_hi:[1,0]
	v_pk_mul_f32 v[106:107], v[110:111], v[106:107]
	v_pk_mul_f32 v[110:111], v[100:101], s[48:49] op_sel_hi:[1,0]
	v_exp_f32_e32 v108, v108
	v_exp_f32_e32 v110, v110
	v_exp_f32_e32 v111, v111
	v_exp_f32_e32 v109, v109
	v_or_b32_e32 v112, 16, v164
	v_mad_i64_i32 v[112:113], s[26:27], v112, s90, v[138:139]
	v_pk_add_f32 v[108:109], v[108:109], 1.0 op_sel_hi:[1,0]
	v_pk_add_f32 v[110:111], v[110:111], 1.0 op_sel_hi:[1,0]
	v_rcp_f32_e32 v102, v108
	v_rcp_f32_e32 v100, v110
	v_rcp_f32_e32 v101, v111
	v_rcp_f32_e32 v103, v109
	v_lshl_add_u64 v[112:113], v[112:113], 0, v[140:141]
	v_pk_mul_f32 v[90:91], v[94:95], v[90:91]
	v_pk_mul_f32 v[88:89], v[92:93], v[88:89]
	v_pk_mul_f32 v[102:103], v[102:103], v[98:99]
	v_pk_mul_f32 v[98:99], v[100:101], v[96:97]
	v_cvt_pk_bf16_f32 v96, v104, v105
	v_cvt_pk_bf16_f32 v97, v106, v107
	v_pk_mul_f32 v[100:101], v[92:93], s[48:49] op_sel_hi:[1,0]
	v_cvt_pk_bf16_f32 v98, v98, v99
	v_cvt_pk_bf16_f32 v99, v102, v103
	global_store_dwordx4 v[112:113], v[96:99], off
	v_exp_f32_e32 v100, v100
	v_exp_f32_e32 v101, v101
	v_pk_mul_f32 v[98:99], v[94:95], s[48:49] op_sel_hi:[1,0]
	v_pk_mul_f32 v[82:83], v[86:87], v[82:83]
	v_exp_f32_e32 v98, v98
	v_exp_f32_e32 v99, v99
	v_pk_add_f32 v[100:101], v[100:101], 1.0 op_sel_hi:[1,0]
	v_pk_mul_f32 v[80:81], v[84:85], v[80:81]
	v_rcp_f32_e32 v92, v100
	v_pk_add_f32 v[98:99], v[98:99], 1.0 op_sel_hi:[1,0]
	v_rcp_f32_e32 v93, v101
	v_rcp_f32_e32 v94, v98
	v_rcp_f32_e32 v95, v99
	v_or_b32_e32 v96, 32, v164
	v_pk_mul_f32 v[88:89], v[92:93], v[88:89]
	v_pk_mul_f32 v[92:93], v[86:87], s[48:49] op_sel_hi:[1,0]
	v_pk_mul_f32 v[90:91], v[94:95], v[90:91]
	v_pk_mul_f32 v[94:95], v[84:85], s[48:49] op_sel_hi:[1,0]
	v_exp_f32_e32 v92, v92
	v_exp_f32_e32 v94, v94
	v_exp_f32_e32 v95, v95
	v_exp_f32_e32 v93, v93
	v_mad_i64_i32 v[96:97], s[26:27], v96, s90, v[138:139]
	v_pk_add_f32 v[94:95], v[94:95], 1.0 op_sel_hi:[1,0]
	v_pk_add_f32 v[92:93], v[92:93], 1.0 op_sel_hi:[1,0]
	v_rcp_f32_e32 v84, v94
	v_rcp_f32_e32 v85, v95
	v_rcp_f32_e32 v86, v92
	v_rcp_f32_e32 v87, v93
	v_lshl_add_u64 v[96:97], v[96:97], 0, v[140:141]
	v_pk_mul_f32 v[74:75], v[78:79], v[74:75]
	v_pk_mul_f32 v[72:73], v[76:77], v[72:73]
	v_pk_mul_f32 v[86:87], v[86:87], v[82:83]
	v_pk_mul_f32 v[82:83], v[84:85], v[80:81]
	v_cvt_pk_bf16_f32 v80, v88, v89
	v_cvt_pk_bf16_f32 v81, v90, v91
	v_pk_mul_f32 v[84:85], v[76:77], s[48:49] op_sel_hi:[1,0]
	v_cvt_pk_bf16_f32 v82, v82, v83
	v_cvt_pk_bf16_f32 v83, v86, v87
	global_store_dwordx4 v[96:97], v[80:83], off
	v_exp_f32_e32 v84, v84
	v_exp_f32_e32 v85, v85
	v_pk_mul_f32 v[82:83], v[78:79], s[48:49] op_sel_hi:[1,0]
	v_pk_mul_f32 v[66:67], v[70:71], v[66:67]
	v_exp_f32_e32 v82, v82
	v_exp_f32_e32 v83, v83
	v_pk_add_f32 v[84:85], v[84:85], 1.0 op_sel_hi:[1,0]
	v_pk_mul_f32 v[64:65], v[68:69], v[64:65]
	v_rcp_f32_e32 v76, v84
	v_pk_add_f32 v[82:83], v[82:83], 1.0 op_sel_hi:[1,0]
	v_rcp_f32_e32 v77, v85
	v_rcp_f32_e32 v78, v82
	v_rcp_f32_e32 v79, v83
	v_or_b32_e32 v80, 48, v164
	v_pk_mul_f32 v[72:73], v[76:77], v[72:73]
	v_pk_mul_f32 v[76:77], v[70:71], s[48:49] op_sel_hi:[1,0]
	v_pk_mul_f32 v[74:75], v[78:79], v[74:75]
	v_pk_mul_f32 v[78:79], v[68:69], s[48:49] op_sel_hi:[1,0]
	v_exp_f32_e32 v76, v76
	v_exp_f32_e32 v78, v78
	v_exp_f32_e32 v79, v79
	v_exp_f32_e32 v77, v77
	v_mad_i64_i32 v[80:81], s[26:27], v80, s90, v[138:139]
	v_pk_add_f32 v[78:79], v[78:79], 1.0 op_sel_hi:[1,0]
	v_pk_add_f32 v[76:77], v[76:77], 1.0 op_sel_hi:[1,0]
	v_rcp_f32_e32 v68, v78
	v_rcp_f32_e32 v69, v79
	v_rcp_f32_e32 v70, v76
	v_rcp_f32_e32 v71, v77
	v_lshl_add_u64 v[80:81], v[80:81], 0, v[140:141]
	v_pk_mul_f32 v[58:59], v[62:63], v[58:59]
	v_pk_mul_f32 v[56:57], v[60:61], v[56:57]
	v_pk_mul_f32 v[70:71], v[70:71], v[66:67]
	v_pk_mul_f32 v[66:67], v[68:69], v[64:65]
	v_cvt_pk_bf16_f32 v64, v72, v73
	v_cvt_pk_bf16_f32 v65, v74, v75
	v_pk_mul_f32 v[68:69], v[60:61], s[48:49] op_sel_hi:[1,0]
	v_cvt_pk_bf16_f32 v66, v66, v67
	v_cvt_pk_bf16_f32 v67, v70, v71
	global_store_dwordx4 v[80:81], v[64:67], off
	v_exp_f32_e32 v68, v68
	v_exp_f32_e32 v69, v69
	v_pk_mul_f32 v[66:67], v[62:63], s[48:49] op_sel_hi:[1,0]
	v_pk_mul_f32 v[50:51], v[54:55], v[50:51]
	v_exp_f32_e32 v66, v66
	v_exp_f32_e32 v67, v67
	v_pk_add_f32 v[68:69], v[68:69], 1.0 op_sel_hi:[1,0]
	v_pk_mul_f32 v[48:49], v[52:53], v[48:49]
	v_rcp_f32_e32 v60, v68
	v_pk_add_f32 v[66:67], v[66:67], 1.0 op_sel_hi:[1,0]
	v_rcp_f32_e32 v61, v69
	v_rcp_f32_e32 v62, v66
	v_rcp_f32_e32 v63, v67
	v_add_u32_e32 v64, 0x80, v164
	v_pk_mul_f32 v[56:57], v[60:61], v[56:57]
	v_pk_mul_f32 v[60:61], v[54:55], s[48:49] op_sel_hi:[1,0]
	v_pk_mul_f32 v[58:59], v[62:63], v[58:59]
	v_pk_mul_f32 v[62:63], v[52:53], s[48:49] op_sel_hi:[1,0]
	v_exp_f32_e32 v60, v60
	v_exp_f32_e32 v62, v62
	v_exp_f32_e32 v63, v63
	v_exp_f32_e32 v61, v61
	v_mad_i64_i32 v[64:65], s[26:27], v64, s90, v[138:139]
	v_pk_add_f32 v[62:63], v[62:63], 1.0 op_sel_hi:[1,0]
	v_pk_add_f32 v[60:61], v[60:61], 1.0 op_sel_hi:[1,0]
	v_rcp_f32_e32 v52, v62
	v_rcp_f32_e32 v53, v63
	v_rcp_f32_e32 v54, v60
	v_rcp_f32_e32 v55, v61
	v_lshl_add_u64 v[64:65], v[64:65], 0, v[140:141]
	v_pk_mul_f32 v[42:43], v[46:47], v[42:43]
	v_pk_mul_f32 v[40:41], v[44:45], v[40:41]
	v_pk_mul_f32 v[54:55], v[54:55], v[50:51]
	v_pk_mul_f32 v[50:51], v[52:53], v[48:49]
	v_cvt_pk_bf16_f32 v48, v56, v57
	v_cvt_pk_bf16_f32 v49, v58, v59
	v_pk_mul_f32 v[52:53], v[44:45], s[48:49] op_sel_hi:[1,0]
	v_cvt_pk_bf16_f32 v50, v50, v51
	v_cvt_pk_bf16_f32 v51, v54, v55
	global_store_dwordx4 v[64:65], v[48:51], off
	v_exp_f32_e32 v52, v52
	v_exp_f32_e32 v53, v53
	v_pk_mul_f32 v[50:51], v[46:47], s[48:49] op_sel_hi:[1,0]
	v_pk_mul_f32 v[34:35], v[38:39], v[34:35]
	v_exp_f32_e32 v50, v50
	v_exp_f32_e32 v51, v51
	v_pk_add_f32 v[52:53], v[52:53], 1.0 op_sel_hi:[1,0]
	v_pk_mul_f32 v[32:33], v[36:37], v[32:33]
	v_rcp_f32_e32 v44, v52
	v_pk_add_f32 v[50:51], v[50:51], 1.0 op_sel_hi:[1,0]
	v_rcp_f32_e32 v45, v53
	v_rcp_f32_e32 v46, v50
	v_rcp_f32_e32 v47, v51
	v_add_u32_e32 v48, 0x90, v164
	v_pk_mul_f32 v[40:41], v[44:45], v[40:41]
	v_pk_mul_f32 v[44:45], v[38:39], s[48:49] op_sel_hi:[1,0]
	v_pk_mul_f32 v[42:43], v[46:47], v[42:43]
	v_pk_mul_f32 v[46:47], v[36:37], s[48:49] op_sel_hi:[1,0]
	v_exp_f32_e32 v44, v44
	v_exp_f32_e32 v46, v46
	v_exp_f32_e32 v47, v47
	v_exp_f32_e32 v45, v45
	v_mad_i64_i32 v[48:49], s[26:27], v48, s90, v[138:139]
	v_pk_add_f32 v[46:47], v[46:47], 1.0 op_sel_hi:[1,0]
	v_pk_add_f32 v[44:45], v[44:45], 1.0 op_sel_hi:[1,0]
	v_rcp_f32_e32 v36, v46
	v_rcp_f32_e32 v37, v47
	v_rcp_f32_e32 v38, v44
	v_rcp_f32_e32 v39, v45
	v_lshl_add_u64 v[48:49], v[48:49], 0, v[140:141]
	v_pk_mul_f32 v[26:27], v[30:31], v[26:27]
	v_pk_mul_f32 v[24:25], v[28:29], v[24:25]
	v_pk_mul_f32 v[38:39], v[38:39], v[34:35]
	v_pk_mul_f32 v[34:35], v[36:37], v[32:33]
	v_cvt_pk_bf16_f32 v32, v40, v41
	v_cvt_pk_bf16_f32 v33, v42, v43
	v_pk_mul_f32 v[36:37], v[28:29], s[48:49] op_sel_hi:[1,0]
	v_cvt_pk_bf16_f32 v34, v34, v35
	v_cvt_pk_bf16_f32 v35, v38, v39
	global_store_dwordx4 v[48:49], v[32:35], off
	v_exp_f32_e32 v36, v36
	v_exp_f32_e32 v37, v37
	v_pk_mul_f32 v[34:35], v[30:31], s[48:49] op_sel_hi:[1,0]
	v_pk_mul_f32 v[18:19], v[22:23], v[18:19]
	v_exp_f32_e32 v34, v34
	v_exp_f32_e32 v35, v35
	v_pk_add_f32 v[36:37], v[36:37], 1.0 op_sel_hi:[1,0]
	v_pk_mul_f32 v[16:17], v[20:21], v[16:17]
	v_rcp_f32_e32 v28, v36
	v_pk_add_f32 v[34:35], v[34:35], 1.0 op_sel_hi:[1,0]
	v_rcp_f32_e32 v29, v37
	v_rcp_f32_e32 v30, v34
	v_rcp_f32_e32 v31, v35
	v_add_u32_e32 v32, 0xa0, v164
	v_pk_mul_f32 v[24:25], v[28:29], v[24:25]
	v_pk_mul_f32 v[28:29], v[22:23], s[48:49] op_sel_hi:[1,0]
	v_pk_mul_f32 v[26:27], v[30:31], v[26:27]
	v_pk_mul_f32 v[30:31], v[20:21], s[48:49] op_sel_hi:[1,0]
	v_exp_f32_e32 v28, v28
	v_exp_f32_e32 v30, v30
	v_exp_f32_e32 v31, v31
	v_exp_f32_e32 v29, v29
	v_mad_i64_i32 v[32:33], s[26:27], v32, s90, v[138:139]
	v_pk_add_f32 v[30:31], v[30:31], 1.0 op_sel_hi:[1,0]
	v_pk_add_f32 v[28:29], v[28:29], 1.0 op_sel_hi:[1,0]
	v_rcp_f32_e32 v20, v30
	v_rcp_f32_e32 v21, v31
	v_rcp_f32_e32 v22, v28
	v_rcp_f32_e32 v23, v29
	v_lshl_add_u64 v[32:33], v[32:33], 0, v[140:141]
	v_pk_mul_f32 v[10:11], v[14:15], v[10:11]
	v_pk_mul_f32 v[8:9], v[12:13], v[8:9]
	v_pk_mul_f32 v[22:23], v[22:23], v[18:19]
	v_pk_mul_f32 v[18:19], v[20:21], v[16:17]
	v_cvt_pk_bf16_f32 v16, v24, v25
	v_cvt_pk_bf16_f32 v17, v26, v27
	v_pk_mul_f32 v[20:21], v[12:13], s[48:49] op_sel_hi:[1,0]
	v_cvt_pk_bf16_f32 v18, v18, v19
	v_cvt_pk_bf16_f32 v19, v22, v23
	global_store_dwordx4 v[32:33], v[16:19], off
	v_exp_f32_e32 v20, v20
	v_exp_f32_e32 v21, v21
	v_pk_mul_f32 v[18:19], v[14:15], s[48:49] op_sel_hi:[1,0]
	v_pk_mul_f32 v[2:3], v[6:7], v[2:3]
	v_exp_f32_e32 v18, v18
	v_exp_f32_e32 v19, v19
	v_pk_add_f32 v[20:21], v[20:21], 1.0 op_sel_hi:[1,0]
	v_pk_mul_f32 v[0:1], v[4:5], v[0:1]
	v_rcp_f32_e32 v12, v20
	v_pk_add_f32 v[18:19], v[18:19], 1.0 op_sel_hi:[1,0]
	v_rcp_f32_e32 v13, v21
	v_rcp_f32_e32 v14, v18
	v_rcp_f32_e32 v15, v19
	v_add_u32_e32 v16, 0xb0, v164
	v_pk_mul_f32 v[8:9], v[12:13], v[8:9]
	v_pk_mul_f32 v[12:13], v[6:7], s[48:49] op_sel_hi:[1,0]
	v_pk_mul_f32 v[10:11], v[14:15], v[10:11]
	v_pk_mul_f32 v[14:15], v[4:5], s[48:49] op_sel_hi:[1,0]
	v_exp_f32_e32 v12, v12
	v_exp_f32_e32 v14, v14
	v_exp_f32_e32 v15, v15
	v_exp_f32_e32 v13, v13
	v_mad_i64_i32 v[16:17], s[26:27], v16, s90, v[138:139]
	v_pk_add_f32 v[14:15], v[14:15], 1.0 op_sel_hi:[1,0]
	v_pk_add_f32 v[12:13], v[12:13], 1.0 op_sel_hi:[1,0]
	v_rcp_f32_e32 v4, v14
	v_rcp_f32_e32 v5, v15
	v_rcp_f32_e32 v6, v12
	v_rcp_f32_e32 v7, v13
	v_lshl_add_u64 v[16:17], v[16:17], 0, v[140:141]
	s_and_b64 vcc, exec, s[4:5]
	s_mov_b32 s57, s56
	v_pk_mul_f32 v[6:7], v[6:7], v[2:3]
	v_pk_mul_f32 v[2:3], v[4:5], v[0:1]
	s_mov_b32 s66, s20
	s_mov_b64 s[28:29], s[8:9]
	s_mov_b64 s[26:27], s[6:7]
	v_cvt_pk_bf16_f32 v0, v8, v9
	v_cvt_pk_bf16_f32 v1, v10, v11
	v_cvt_pk_bf16_f32 v2, v2, v3
	v_cvt_pk_bf16_f32 v3, v6, v7
	global_store_dwordx4 v[16:17], v[0:3], off
	s_cbranch_vccz .LBB0_693
	s_waitcnt vmcnt(0)
	s_cmpk_gt_u32 s18, 0xff
	s_mov_b32 s55, 0xbc00000
	s_cbranch_scc1 .LBB0_704
	s_barrier

.LBB0_773:
	s_add_i32 s83, s28, 2
	s_add_u32 s30, s16, 0x80
	s_addc_u32 s29, s17, 0
	s_add_i32 s88, 0, 0x10000
	v_add_u32_e32 v138, s88, v141
	ds_read_b128 v[162:165], v138
	ds_read_b128 v[166:169], v138 offset:1024
	ds_read_b128 v[170:173], v138 offset:2048
	ds_read_b128 v[174:177], v138 offset:3072
	s_cmp_eq_u32 s67, s28
	s_cselect_b32 s28, s6, s30
	s_cselect_b32 s29, s7, s29
	s_cselect_b32 s31, s9, s82
	s_cselect_b32 s30, s8, s75
	v_lshl_add_u64 v[138:139], s[16:17], 0, v[134:135]
	s_add_i32 m0, s37, 0xc000
	ds_read_b128 v[178:181], v143
	ds_read_b128 v[198:201], v143 offset:2048
	ds_read_b128 v[206:209], v143 offset:4096
	ds_read_b128 v[214:217], v143 offset:6144
	global_load_lds_dwordx4 v[138:139], off
	v_lshl_add_u64 v[138:139], s[16:17], 0, v[136:137]
	s_add_i32 m0, s37, 0xe000
	s_nop 0
	global_load_lds_dwordx4 v[138:139], off
	s_waitcnt lgkmcnt(4)
	s_barrier
	s_setprio 1
	ds_read_b128 v[194:197], v143 offset:1024
	ds_read_b128 v[202:205], v143 offset:3072
	ds_read_b128 v[210:213], v143 offset:5120
	ds_read_b128 v[218:221], v143 offset:7168
	s_waitcnt lgkmcnt(7)
	v_mfma_f32_16x16x32_bf16 v[124:127], v[162:165], v[178:181], v[124:127]
	v_mfma_f32_16x16x32_bf16 v[120:123], v[170:173], v[178:181], v[120:123]
	s_waitcnt lgkmcnt(6)
	v_mfma_f32_16x16x32_bf16 v[116:119], v[162:165], v[198:201], v[116:119]
	v_mfma_f32_16x16x32_bf16 v[108:111], v[170:173], v[198:201], v[108:111]
	s_waitcnt lgkmcnt(5)
	v_mfma_f32_16x16x32_bf16 v[100:103], v[162:165], v[206:209], v[100:103]
	v_mfma_f32_16x16x32_bf16 v[92:95], v[170:173], v[206:209], v[92:95]
	s_waitcnt lgkmcnt(4)
	v_mfma_f32_16x16x32_bf16 v[84:87], v[162:165], v[214:217], v[84:87]
	v_mfma_f32_16x16x32_bf16 v[76:79], v[170:173], v[214:217], v[76:79]
	s_waitcnt lgkmcnt(3)
	v_mfma_f32_16x16x32_bf16 v[124:127], v[166:169], v[194:197], v[124:127]
	v_mfma_f32_16x16x32_bf16 v[120:123], v[174:177], v[194:197], v[120:123]
	s_waitcnt lgkmcnt(2)
	v_mfma_f32_16x16x32_bf16 v[116:119], v[166:169], v[202:205], v[116:119]
	v_mfma_f32_16x16x32_bf16 v[108:111], v[174:177], v[202:205], v[108:111]
	s_waitcnt lgkmcnt(1)
	v_mfma_f32_16x16x32_bf16 v[100:103], v[166:169], v[210:213], v[100:103]
	v_mfma_f32_16x16x32_bf16 v[92:95], v[174:177], v[210:213], v[92:95]
	s_waitcnt lgkmcnt(0)
	v_mfma_f32_16x16x32_bf16 v[84:87], v[166:169], v[218:221], v[84:87]
	v_mfma_f32_16x16x32_bf16 v[76:79], v[174:177], v[218:221], v[76:79]
	s_setprio 0
	s_barrier
	s_add_i32 s89, 0, 0x14000
	v_add_u32_e32 v138, s89, v141
	s_add_i32 s88, s88, s36
	ds_read_b128 v[222:225], v138
	ds_read_b128 v[226:229], v138 offset:1024
	ds_read_b128 v[230:233], v138 offset:2048
	ds_read_b128 v[234:237], v138 offset:3072
	v_lshl_add_u64 v[138:139], s[30:31], 0, v[144:145]
	s_mov_b32 m0, s88
	v_lshl_add_u64 v[238:239], s[30:31], 0, v[128:129]
	global_load_lds_dwordx4 v[138:139], off
	s_add_i32 m0, s88, 0x2000
	s_nop 0
	global_load_lds_dwordx4 v[238:239], off
	s_barrier
	s_setprio 1
	s_waitcnt lgkmcnt(3)
	v_mfma_f32_16x16x32_bf16 v[112:115], v[222:225], v[178:181], v[112:115]
	s_waitcnt lgkmcnt(1)
	v_mfma_f32_16x16x32_bf16 v[104:107], v[230:233], v[178:181], v[104:107]
	v_mfma_f32_16x16x32_bf16 v[96:99], v[222:225], v[198:201], v[96:99]
	v_mfma_f32_16x16x32_bf16 v[88:91], v[230:233], v[198:201], v[88:91]
	v_mfma_f32_16x16x32_bf16 v[80:83], v[222:225], v[206:209], v[80:83]
	v_mfma_f32_16x16x32_bf16 v[72:75], v[230:233], v[206:209], v[72:75]
	v_mfma_f32_16x16x32_bf16 v[68:71], v[222:225], v[214:217], v[68:71]
	v_mfma_f32_16x16x32_bf16 v[64:67], v[230:233], v[214:217], v[64:67]
	v_mfma_f32_16x16x32_bf16 v[112:115], v[226:229], v[194:197], v[112:115]
	s_waitcnt lgkmcnt(0)
	v_mfma_f32_16x16x32_bf16 v[104:107], v[234:237], v[194:197], v[104:107]
	v_mfma_f32_16x16x32_bf16 v[96:99], v[226:229], v[202:205], v[96:99]
	v_mfma_f32_16x16x32_bf16 v[88:91], v[234:237], v[202:205], v[88:91]
	v_mfma_f32_16x16x32_bf16 v[80:83], v[226:229], v[210:213], v[80:83]
	v_mfma_f32_16x16x32_bf16 v[72:75], v[234:237], v[210:213], v[72:75]
	v_mfma_f32_16x16x32_bf16 v[68:71], v[226:229], v[218:221], v[68:71]
	v_mfma_f32_16x16x32_bf16 v[64:67], v[234:237], v[218:221], v[64:67]
	s_setprio 0
	s_mov_b32 m0, s37
	v_lshl_add_u64 v[240:241], s[28:29], 0, v[132:133]
	s_barrier
	ds_read_b128 v[178:181], v143 offset:16384
	ds_read_b128 v[194:197], v143 offset:17408
	ds_read_b128 v[198:201], v143 offset:18432
	ds_read_b128 v[202:205], v143 offset:19456
	ds_read_b128 v[206:209], v143 offset:20480
	ds_read_b128 v[210:213], v143 offset:21504
	ds_read_b128 v[214:217], v143 offset:22528
	ds_read_b128 v[218:221], v143 offset:23552
	global_load_lds_dwordx4 v[240:241], off
	v_lshl_add_u64 v[242:243], s[28:29], 0, v[130:131]
	s_mov_b32 m0, s50
	s_nop 0
	global_load_lds_dwordx4 v[242:243], off
	s_barrier
	s_setprio 1
	s_waitcnt lgkmcnt(7)
	v_mfma_f32_16x16x32_bf16 v[60:63], v[162:165], v[178:181], v[60:63]
	v_mfma_f32_16x16x32_bf16 v[56:59], v[170:173], v[178:181], v[56:59]
	s_waitcnt lgkmcnt(5)
	v_mfma_f32_16x16x32_bf16 v[52:55], v[162:165], v[198:201], v[52:55]
	v_mfma_f32_16x16x32_bf16 v[48:51], v[170:173], v[198:201], v[48:51]
	s_waitcnt lgkmcnt(3)
	v_mfma_f32_16x16x32_bf16 v[36:39], v[162:165], v[206:209], v[36:39]
	v_mfma_f32_16x16x32_bf16 v[32:35], v[170:173], v[206:209], v[32:35]
	s_waitcnt lgkmcnt(1)
	v_mfma_f32_16x16x32_bf16 v[20:23], v[162:165], v[214:217], v[20:23]
	v_mfma_f32_16x16x32_bf16 v[16:19], v[170:173], v[214:217], v[16:19]
	v_mfma_f32_16x16x32_bf16 v[60:63], v[166:169], v[194:197], v[60:63]
	v_mfma_f32_16x16x32_bf16 v[56:59], v[174:177], v[194:197], v[56:59]
	v_mfma_f32_16x16x32_bf16 v[52:55], v[166:169], v[202:205], v[52:55]
	v_mfma_f32_16x16x32_bf16 v[48:51], v[174:177], v[202:205], v[48:51]
	v_mfma_f32_16x16x32_bf16 v[36:39], v[166:169], v[210:213], v[36:39]
	v_mfma_f32_16x16x32_bf16 v[32:35], v[174:177], v[210:213], v[32:35]
	s_waitcnt lgkmcnt(0)
	v_mfma_f32_16x16x32_bf16 v[20:23], v[166:169], v[218:221], v[20:23]
	v_mfma_f32_16x16x32_bf16 v[16:19], v[174:177], v[218:221], v[16:19]
	s_setprio 0
	s_barrier
	s_add_u32 s30, s30, s76
	s_addc_u32 s31, s31, 0
	s_add_i32 s88, s89, s36
	v_lshl_add_u64 v[244:245], s[30:31], 0, v[144:145]
	s_mov_b32 m0, s88
	v_lshl_add_u64 v[246:247], s[30:31], 0, v[128:129]
	global_load_lds_dwordx4 v[244:245], off
	s_add_i32 m0, s88, 0x2000
	s_nop 0
	global_load_lds_dwordx4 v[246:247], off
	s_waitcnt vmcnt(6)
	s_barrier
	s_setprio 1
	v_mfma_f32_16x16x32_bf16 v[44:47], v[222:225], v[178:181], v[44:47]
	v_mfma_f32_16x16x32_bf16 v[40:43], v[230:233], v[178:181], v[40:43]
	v_mfma_f32_16x16x32_bf16 v[28:31], v[222:225], v[198:201], v[28:31]
	v_mfma_f32_16x16x32_bf16 v[24:27], v[230:233], v[198:201], v[24:27]
	v_mfma_f32_16x16x32_bf16 v[12:15], v[222:225], v[206:209], v[12:15]
	v_mfma_f32_16x16x32_bf16 v[8:11], v[230:233], v[206:209], v[8:11]
	v_mfma_f32_16x16x32_bf16 v[4:7], v[222:225], v[214:217], v[4:7]
	v_mfma_f32_16x16x32_bf16 v[0:3], v[230:233], v[214:217], v[0:3]
	v_mfma_f32_16x16x32_bf16 v[44:47], v[226:229], v[194:197], v[44:47]
	v_mfma_f32_16x16x32_bf16 v[40:43], v[234:237], v[194:197], v[40:43]
	v_mfma_f32_16x16x32_bf16 v[28:31], v[226:229], v[202:205], v[28:31]
	v_mfma_f32_16x16x32_bf16 v[24:27], v[234:237], v[202:205], v[24:27]
	v_mfma_f32_16x16x32_bf16 v[12:15], v[226:229], v[210:213], v[12:15]
	v_mfma_f32_16x16x32_bf16 v[8:11], v[234:237], v[210:213], v[8:11]
	v_mfma_f32_16x16x32_bf16 v[4:7], v[226:229], v[218:221], v[4:7]
	v_mfma_f32_16x16x32_bf16 v[0:3], v[234:237], v[218:221], v[0:3]
	s_setprio 0
	s_add_i32 s30, 0, 0x18000
	v_add_u32_e32 v174, s30, v141
	s_barrier
	ds_read_b128 v[162:165], v174
	ds_read_b128 v[166:169], v174 offset:1024
	ds_read_b128 v[170:173], v174 offset:2048
	ds_read_b128 v[174:177], v174 offset:3072
	s_add_u32 s28, s28, s76
	s_addc_u32 s29, s29, 0
	s_mov_b32 m0, s51
	v_lshl_add_u64 v[222:223], s[28:29], 0, v[132:133]
	ds_read_b128 v[178:181], v143 offset:32768
	ds_read_b128 v[198:201], v143 offset:34816
	ds_read_b128 v[206:209], v143 offset:36864
	ds_read_b128 v[214:217], v143 offset:38912
	global_load_lds_dwordx4 v[222:223], off
	v_lshl_add_u64 v[222:223], s[28:29], 0, v[130:131]
	s_mov_b32 m0, s54
	s_nop 0
	global_load_lds_dwordx4 v[222:223], off
	s_waitcnt lgkmcnt(4)
	s_barrier
	s_setprio 1
	ds_read_b128 v[194:197], v143 offset:33792
	ds_read_b128 v[202:205], v143 offset:35840
	ds_read_b128 v[210:213], v143 offset:37888
	ds_read_b128 v[218:221], v143 offset:39936
	s_waitcnt lgkmcnt(7)
	v_mfma_f32_16x16x32_bf16 v[124:127], v[162:165], v[178:181], v[124:127]
	v_mfma_f32_16x16x32_bf16 v[120:123], v[170:173], v[178:181], v[120:123]
	s_waitcnt lgkmcnt(6)
	v_mfma_f32_16x16x32_bf16 v[116:119], v[162:165], v[198:201], v[116:119]
	v_mfma_f32_16x16x32_bf16 v[108:111], v[170:173], v[198:201], v[108:111]
	s_waitcnt lgkmcnt(5)
	v_mfma_f32_16x16x32_bf16 v[100:103], v[162:165], v[206:209], v[100:103]
	v_mfma_f32_16x16x32_bf16 v[92:95], v[170:173], v[206:209], v[92:95]
	s_waitcnt lgkmcnt(4)
	v_mfma_f32_16x16x32_bf16 v[84:87], v[162:165], v[214:217], v[84:87]
	v_mfma_f32_16x16x32_bf16 v[76:79], v[170:173], v[214:217], v[76:79]
	s_waitcnt lgkmcnt(3)
	v_mfma_f32_16x16x32_bf16 v[124:127], v[166:169], v[194:197], v[124:127]
	v_mfma_f32_16x16x32_bf16 v[120:123], v[174:177], v[194:197], v[120:123]
	s_waitcnt lgkmcnt(2)
	v_mfma_f32_16x16x32_bf16 v[116:119], v[166:169], v[202:205], v[116:119]
	v_mfma_f32_16x16x32_bf16 v[108:111], v[174:177], v[202:205], v[108:111]
	s_waitcnt lgkmcnt(1)
	v_mfma_f32_16x16x32_bf16 v[100:103], v[166:169], v[210:213], v[100:103]
	v_mfma_f32_16x16x32_bf16 v[92:95], v[174:177], v[210:213], v[92:95]
	s_waitcnt lgkmcnt(0)
	v_mfma_f32_16x16x32_bf16 v[84:87], v[166:169], v[218:221], v[84:87]
	v_mfma_f32_16x16x32_bf16 v[76:79], v[174:177], v[218:221], v[76:79]
	s_setprio 0
	s_barrier
	s_add_i32 s28, 0, 0x1c000
	s_add_i32 s29, s30, s36
	v_add_u32_e32 v193, s28, v141
	v_lshl_add_u64 v[138:139], v[138:139], 0, s[86:87]
	s_mov_b32 m0, s29
	ds_read_b128 v[222:225], v193
	ds_read_b128 v[226:229], v193 offset:1024
	ds_read_b128 v[230:233], v193 offset:2048
	ds_read_b128 v[234:237], v193 offset:3072
	global_load_lds_dwordx4 v[138:139], off
	v_lshl_add_u64 v[138:139], v[238:239], 0, s[86:87]
	s_add_i32 m0, s29, 0x2000
	s_nop 0
	global_load_lds_dwordx4 v[138:139], off
	s_barrier
	s_setprio 1
	s_waitcnt lgkmcnt(3)
	v_mfma_f32_16x16x32_bf16 v[112:115], v[222:225], v[178:181], v[112:115]
	s_waitcnt lgkmcnt(1)
	v_mfma_f32_16x16x32_bf16 v[104:107], v[230:233], v[178:181], v[104:107]
	v_mfma_f32_16x16x32_bf16 v[96:99], v[222:225], v[198:201], v[96:99]
	v_mfma_f32_16x16x32_bf16 v[88:91], v[230:233], v[198:201], v[88:91]
	v_mfma_f32_16x16x32_bf16 v[80:83], v[222:225], v[206:209], v[80:83]
	v_mfma_f32_16x16x32_bf16 v[72:75], v[230:233], v[206:209], v[72:75]
	v_mfma_f32_16x16x32_bf16 v[68:71], v[222:225], v[214:217], v[68:71]
	v_mfma_f32_16x16x32_bf16 v[64:67], v[230:233], v[214:217], v[64:67]
	v_mfma_f32_16x16x32_bf16 v[112:115], v[226:229], v[194:197], v[112:115]
	s_waitcnt lgkmcnt(0)
	v_mfma_f32_16x16x32_bf16 v[104:107], v[234:237], v[194:197], v[104:107]
	v_mfma_f32_16x16x32_bf16 v[96:99], v[226:229], v[202:205], v[96:99]
	v_mfma_f32_16x16x32_bf16 v[88:91], v[234:237], v[202:205], v[88:91]
	v_mfma_f32_16x16x32_bf16 v[80:83], v[226:229], v[210:213], v[80:83]
	v_mfma_f32_16x16x32_bf16 v[72:75], v[234:237], v[210:213], v[72:75]
	v_mfma_f32_16x16x32_bf16 v[68:71], v[226:229], v[218:221], v[68:71]
	v_mfma_f32_16x16x32_bf16 v[64:67], v[234:237], v[218:221], v[64:67]
	s_setprio 0
	s_mov_b32 m0, s57
	v_lshl_add_u64 v[138:139], v[240:241], 0, s[86:87]
	s_barrier
	ds_read_b128 v[178:181], v143 offset:49152
	ds_read_b128 v[194:197], v143 offset:50176
	ds_read_b128 v[198:201], v143 offset:51200
	ds_read_b128 v[202:205], v143 offset:52224
	ds_read_b128 v[206:209], v143 offset:53248
	ds_read_b128 v[210:213], v143 offset:54272
	ds_read_b128 v[214:217], v143 offset:55296
	ds_read_b128 v[218:221], v143 offset:56320
	global_load_lds_dwordx4 v[138:139], off
	v_lshl_add_u64 v[138:139], v[242:243], 0, s[86:87]
	s_mov_b32 m0, s66
	s_nop 0
	global_load_lds_dwordx4 v[138:139], off
	s_barrier
	s_setprio 1
	s_waitcnt lgkmcnt(7)
	v_mfma_f32_16x16x32_bf16 v[60:63], v[162:165], v[178:181], v[60:63]
	v_mfma_f32_16x16x32_bf16 v[56:59], v[170:173], v[178:181], v[56:59]
	s_waitcnt lgkmcnt(5)
	v_mfma_f32_16x16x32_bf16 v[52:55], v[162:165], v[198:201], v[52:55]
	v_mfma_f32_16x16x32_bf16 v[48:51], v[170:173], v[198:201], v[48:51]
	s_waitcnt lgkmcnt(3)
	v_mfma_f32_16x16x32_bf16 v[36:39], v[162:165], v[206:209], v[36:39]
	v_mfma_f32_16x16x32_bf16 v[32:35], v[170:173], v[206:209], v[32:35]
	s_waitcnt lgkmcnt(1)
	v_mfma_f32_16x16x32_bf16 v[20:23], v[162:165], v[214:217], v[20:23]
	v_mfma_f32_16x16x32_bf16 v[16:19], v[170:173], v[214:217], v[16:19]
	v_mfma_f32_16x16x32_bf16 v[60:63], v[166:169], v[194:197], v[60:63]
	v_mfma_f32_16x16x32_bf16 v[56:59], v[174:177], v[194:197], v[56:59]
	v_mfma_f32_16x16x32_bf16 v[52:55], v[166:169], v[202:205], v[52:55]
	v_mfma_f32_16x16x32_bf16 v[48:51], v[174:177], v[202:205], v[48:51]
	v_mfma_f32_16x16x32_bf16 v[36:39], v[166:169], v[210:213], v[36:39]
	v_mfma_f32_16x16x32_bf16 v[32:35], v[174:177], v[210:213], v[32:35]
	s_waitcnt lgkmcnt(0)
	v_mfma_f32_16x16x32_bf16 v[20:23], v[166:169], v[218:221], v[20:23]
	v_mfma_f32_16x16x32_bf16 v[16:19], v[174:177], v[218:221], v[16:19]
	s_setprio 0
	s_barrier
	s_add_i32 s28, s28, s36
	v_lshl_add_u64 v[138:139], v[244:245], 0, s[86:87]
	s_mov_b32 m0, s28
	s_nop 0
	global_load_lds_dwordx4 v[138:139], off
	v_lshl_add_u64 v[138:139], v[246:247], 0, s[86:87]
	s_add_i32 m0, s28, 0x2000
	s_nop 0
	global_load_lds_dwordx4 v[138:139], off
	s_waitcnt vmcnt(6)
	s_barrier
	s_setprio 1
	v_mfma_f32_16x16x32_bf16 v[44:47], v[222:225], v[178:181], v[44:47]
	v_mfma_f32_16x16x32_bf16 v[40:43], v[230:233], v[178:181], v[40:43]
	v_mfma_f32_16x16x32_bf16 v[28:31], v[222:225], v[198:201], v[28:31]
	v_mfma_f32_16x16x32_bf16 v[24:27], v[230:233], v[198:201], v[24:27]
	v_mfma_f32_16x16x32_bf16 v[12:15], v[222:225], v[206:209], v[12:15]
	v_mfma_f32_16x16x32_bf16 v[8:11], v[230:233], v[206:209], v[8:11]
	v_mfma_f32_16x16x32_bf16 v[4:7], v[222:225], v[214:217], v[4:7]
	v_mfma_f32_16x16x32_bf16 v[0:3], v[230:233], v[214:217], v[0:3]
	v_mfma_f32_16x16x32_bf16 v[44:47], v[226:229], v[194:197], v[44:47]
	v_mfma_f32_16x16x32_bf16 v[40:43], v[234:237], v[194:197], v[40:43]
	v_mfma_f32_16x16x32_bf16 v[28:31], v[226:229], v[202:205], v[28:31]
	v_mfma_f32_16x16x32_bf16 v[24:27], v[234:237], v[202:205], v[24:27]
	v_mfma_f32_16x16x32_bf16 v[12:15], v[226:229], v[210:213], v[12:15]
	v_mfma_f32_16x16x32_bf16 v[8:11], v[234:237], v[210:213], v[8:11]
	v_mfma_f32_16x16x32_bf16 v[4:7], v[226:229], v[218:221], v[4:7]
	v_mfma_f32_16x16x32_bf16 v[0:3], v[234:237], v[218:221], v[0:3]
	s_setprio 0
	s_add_u32 s16, s16, 0x100
	s_addc_u32 s17, s17, 0
	s_add_u32 s75, s75, 0x100
	s_addc_u32 s82, s82, 0
	s_cmp_ge_u32 s83, s56
	s_mov_b32 s28, s83
	s_barrier
	s_cbranch_scc0 .LBB0_773
	s_ashr_i32 s16, s73, 31
	s_lshr_b32 s16, s16, 29
	s_add_i32 s16, s73, s16
	s_and_b32 s16, s16, 0xfffff8
	s_sub_i32 s16, s73, s16
	v_lshl_add_u32 v162, s74, 8, v140
	v_lshl_or_b32 v138, s16, 8, v142
	v_ashrrev_i32_e32 v139, 31, v138
	v_ashrrev_i32_e32 v163, 31, v162
	v_lshl_add_u64 v[164:165], v[138:139], 1, s[10:11]
	v_lshlrev_b64 v[138:139], 12, v[162:163]
	v_lshl_add_u64 v[138:139], v[164:165], 0, v[138:139]
	v_cvt_pk_bf16_f32 v60, v60, v61
	v_cvt_pk_bf16_f32 v61, v62, v63
	v_cvt_pk_bf16_f32 v62, v56, v57
	v_add_co_u32_e32 v56, vcc, s3, v138
	v_cvt_pk_bf16_f32 v68, v68, v69
	v_cvt_pk_bf16_f32 v69, v70, v71
	v_cvt_pk_bf16_f32 v70, v64, v65
	v_lshl_add_u64 v[64:65], v[138:139], 0, s[84:85]
	s_nop 0
	v_addc_co_u32_e32 v57, vcc, 0, v139, vcc
	v_cvt_pk_bf16_f32 v44, v44, v45
	v_cvt_pk_bf16_f32 v45, v46, v47
	v_cvt_pk_bf16_f32 v46, v40, v41
	v_cvt_pk_bf16_f32 v47, v42, v43
	global_store_dwordx4 v[64:65], v[44:47], off offset:256
	v_cvt_pk_bf16_f32 v112, v112, v113
	v_cvt_pk_bf16_f32 v113, v114, v115
	v_cvt_pk_bf16_f32 v114, v104, v105
	v_or_b32_e32 v104, 16, v162
	v_cvt_pk_bf16_f32 v28, v28, v29
	s_nop 0
	v_add_co_u32_e32 v46, vcc, s93, v138
	v_lshl_add_u64 v[44:45], v[138:139], 0, s[46:47]
	s_nop 0
	v_addc_co_u32_e32 v47, vcc, 0, v139, vcc
	v_cvt_pk_bf16_f32 v29, v30, v31
	v_cvt_pk_bf16_f32 v30, v24, v25
	v_ashrrev_i32_e32 v105, 31, v104
	v_cvt_pk_bf16_f32 v96, v96, v97
	v_cvt_pk_bf16_f32 v97, v98, v99
	v_cvt_pk_bf16_f32 v98, v88, v89
	v_or_b32_e32 v88, 32, v162
	v_cvt_pk_bf16_f32 v31, v26, v27
	global_store_dwordx4 v[44:45], v[28:31], off offset:256
	v_lshlrev_b64 v[104:105], 12, v[104:105]
	v_ashrrev_i32_e32 v89, 31, v88
	v_add_co_u32_e32 v30, vcc, s97, v138
	v_cvt_pk_bf16_f32 v80, v80, v81
	v_cvt_pk_bf16_f32 v81, v82, v83
	v_cvt_pk_bf16_f32 v82, v72, v73
	v_or_b32_e32 v72, 48, v162
	v_lshl_add_u64 v[28:29], v[138:139], 0, s[42:43]
	v_addc_co_u32_e32 v31, vcc, 0, v139, vcc
	v_cvt_pk_bf16_f32 v12, v12, v13
	v_cvt_pk_bf16_f32 v13, v14, v15
	v_cvt_pk_bf16_f32 v14, v8, v9
	v_cvt_pk_bf16_f32 v115, v106, v107
	global_store_dwordx4 v[138:139], v[112:115], off offset:256
	v_lshlrev_b64 v[88:89], 12, v[88:89]
	v_ashrrev_i32_e32 v73, 31, v72
	v_lshl_add_u64 v[112:113], v[164:165], 0, v[104:105]
	v_cvt_pk_bf16_f32 v15, v10, v11
	global_store_dwordx4 v[28:29], v[12:15], off offset:256
	v_cvt_pk_bf16_f32 v99, v90, v91
	global_store_dwordx4 v[112:113], v[96:99], off offset:256
	v_lshlrev_b64 v[72:73], 12, v[72:73]
	v_add_co_u32_e32 v14, vcc, s91, v138
	v_lshl_add_u64 v[96:97], v[164:165], 0, v[88:89]
	s_nop 0
	v_addc_co_u32_e32 v15, vcc, 0, v139, vcc
	v_cvt_pk_bf16_f32 v83, v74, v75
	global_store_dwordx4 v[96:97], v[80:83], off offset:256
	v_lshl_add_u64 v[12:13], v[138:139], 0, s[62:63]
	s_and_b64 vcc, exec, s[4:5]
	v_lshl_add_u64 v[80:81], v[164:165], 0, v[72:73]
	s_mov_b32 s73, s71
	s_mov_b32 s74, s72
	s_mov_b64 s[28:29], s[8:9]
	s_mov_b64 s[16:17], s[6:7]
	v_cvt_pk_bf16_f32 v124, v124, v125
	v_cvt_pk_bf16_f32 v125, v126, v127
	v_cvt_pk_bf16_f32 v126, v120, v121
	v_cvt_pk_bf16_f32 v127, v122, v123
	global_store_dwordx4 v[138:139], v[124:127], off
	v_cvt_pk_bf16_f32 v104, v116, v117
	v_cvt_pk_bf16_f32 v105, v118, v119
	v_cvt_pk_bf16_f32 v106, v108, v109
	v_cvt_pk_bf16_f32 v107, v110, v111
	global_store_dwordx4 v[112:113], v[104:107], off
	v_cvt_pk_bf16_f32 v88, v100, v101
	v_cvt_pk_bf16_f32 v89, v102, v103
	v_cvt_pk_bf16_f32 v90, v92, v93
	v_cvt_pk_bf16_f32 v91, v94, v95
	global_store_dwordx4 v[96:97], v[88:91], off
	v_cvt_pk_bf16_f32 v72, v84, v85
	v_cvt_pk_bf16_f32 v73, v86, v87
	v_cvt_pk_bf16_f32 v74, v76, v77
	v_cvt_pk_bf16_f32 v75, v78, v79
	global_store_dwordx4 v[80:81], v[72:75], off
	v_cvt_pk_bf16_f32 v71, v66, v67
	global_store_dwordx4 v[80:81], v[68:71], off offset:256
	v_cvt_pk_bf16_f32 v63, v58, v59
	global_store_dwordx4 v[56:57], v[60:63], off
	v_cvt_pk_bf16_f32 v40, v52, v53
	v_cvt_pk_bf16_f32 v41, v54, v55
	v_cvt_pk_bf16_f32 v42, v48, v49
	v_cvt_pk_bf16_f32 v43, v50, v51
	global_store_dwordx4 v[46:47], v[40:43], off
	v_cvt_pk_bf16_f32 v24, v36, v37
	v_cvt_pk_bf16_f32 v25, v38, v39
	v_cvt_pk_bf16_f32 v26, v32, v33
	v_cvt_pk_bf16_f32 v27, v34, v35
	global_store_dwordx4 v[30:31], v[24:27], off
	v_cvt_pk_bf16_f32 v8, v20, v21
	v_cvt_pk_bf16_f32 v9, v22, v23
	v_cvt_pk_bf16_f32 v10, v16, v17
	v_cvt_pk_bf16_f32 v11, v18, v19
	global_store_dwordx4 v[14:15], v[8:11], off
	v_cvt_pk_bf16_f32 v4, v4, v5
	v_cvt_pk_bf16_f32 v5, v6, v7
	v_cvt_pk_bf16_f32 v6, v0, v1
	v_cvt_pk_bf16_f32 v7, v2, v3
	global_store_dwordx4 v[12:13], v[4:7], off offset:256
	s_cbranch_vccz .LBB0_762
	s_waitcnt vmcnt(0)
	s_cmpk_gt_u32 s13, 0xff
	s_mov_b32 s55, 0xbc00000
	s_cbranch_scc1 .LBB0_777
	s_barrier
